# attn: half-tile stagger of waves 4-7 (2 barriers per tile, V DMA after mid barrier), prio 1 on lagging half; mix phase: gain chunks preloaded, gate loads hoisted
# speedup vs baseline: 1.0527x; 1.0073x over previous
.LBB0_237:
	v_mov_b64_e32 v[30:31], v[14:15]
	v_mov_b64_e32 v[28:29], v[12:13]
	v_mov_b64_e32 v[26:27], v[10:11]
	v_mov_b64_e32 v[24:25], v[8:9]
	v_mov_b64_e32 v[22:23], v[6:7]
	v_mov_b64_e32 v[20:21], v[4:5]
	v_mov_b64_e32 v[18:19], v[2:3]
	v_mov_b64_e32 v[16:17], v[0:1]
	global_load_dwordx2 v[64:65], v[184:185], off
	global_load_dwordx4 v[68:71], v[182:183], off offset:448
	global_load_dwordx4 v[72:75], v[182:183], off offset:464
	global_load_dwordx4 v[20:23], v[182:183], off offset:320
	global_load_dwordx4 v[16:19], v[182:183], off offset:336
	s_lshl_b32 s0, s95, 8
	s_and_b32 s96, s0, 0x3f00
	s_mul_i32 s0, s96, 0x2400
	s_add_u32 s4, s57, s0
	s_addc_u32 s5, s59, 0
	s_lshl_b32 s0, s95, 1
	s_and_b32 s66, s0, 0xffffff80
	s_ashr_i32 s67, s66, 31
	s_lshl_b64 s[0:1], s[66:67], 1
	s_add_u32 s0, s4, s0
	s_addc_u32 s1, s5, s1
	s_ashr_i32 s4, s95, 1
	s_and_b32 s4, s4, 0xffffff80
	s_ashr_i32 s5, s4, 31
	s_lshl_b64 s[68:69], s[4:5], 1
	s_add_u32 s72, s75, s68
	s_addc_u32 s73, s76, s69
	s_add_u32 s70, s77, s68
	v_readfirstlane_b32 s97, v177
	s_addc_u32 s71, s78, s69
	s_lshr_b32 s33, s97, 6
	s_lshl_b32 s8, s33, 5
	v_or_b32_e32 v26, s8, v178
	v_mov_b64_e32 v[24:25], s[0:1]
	s_movk_i32 s0, 0x2400
	v_mad_u64_u32 v[24:25], s[0:1], v26, s0, v[24:25]
	v_lshl_add_u64 v[66:67], v[24:25], 0, v[188:189]
	v_cmp_lt_i32_e64 s[0:1], v212, v211
	global_load_dwordx4 v[94:97], v[66:67], off offset:224
	global_load_dwordx4 v[98:101], v[66:67], off offset:160
	v_cndmask_b32_e64 v52, v210, v212, s[0:1]
	v_cmp_lt_i32_e64 s[0:1], v213, v211
	global_load_dwordx4 v[44:47], v[182:183], off
	global_load_dwordx4 v[40:43], v[182:183], off offset:16
	global_load_dwordx4 v[36:39], v[182:183], off offset:64
	global_load_dwordx4 v[32:35], v[182:183], off offset:80
	global_load_dwordx4 v[104:107], v[182:183], off offset:384
	global_load_dwordx4 v[122:125], v[182:183], off offset:400
	global_load_dwordx4 v[126:129], v[66:67], off offset:192
	global_load_dwordx4 v[136:139], v[66:67], off offset:128
	global_load_dwordx4 v[28:31], v[182:183], off offset:256
	global_load_dwordx4 v[24:27], v[182:183], off offset:272
	global_load_dwordx4 v[48:51], v[182:183], off offset:128
	global_load_dwordx4 v[60:63], v[182:183], off offset:144
	global_load_dwordx4 v[140:143], v[182:183], off offset:192
	global_load_dwordx4 v[144:147], v[182:183], off offset:208
	v_cndmask_b32_e64 v53, v210, v213, s[0:1]
	v_cmp_lt_i32_e64 s[0:1], v214, v211
	v_lshlrev_b32_e32 v76, 2, v52
	v_lshlrev_b32_e32 v77, 2, v53
	v_cndmask_b32_e64 v54, v210, v214, s[0:1]
	v_cmp_lt_i32_e64 s[0:1], v215, v211
	v_lshlrev_b32_e32 v78, 2, v54
	v_or_b32_e32 v134, s96, v178
	v_cndmask_b32_e64 v55, v210, v215, s[0:1]
	v_cmp_lt_i32_e64 s[0:1], v216, v211
	v_lshlrev_b32_e32 v90, 2, v55
	s_mov_b32 s4, 0x7fffffc0
	v_cndmask_b32_e64 v56, v210, v216, s[0:1]
	v_cmp_lt_i32_e64 s[0:1], v217, v211
	v_lshlrev_b32_e32 v102, 2, v56
	v_mov_b32_e32 v195, v181
	v_cndmask_b32_e64 v57, v210, v217, s[0:1]
	v_lshlrev_b32_e32 v108, 2, v57
	global_load_dwordx4 v[52:55], v[66:67], off
	global_load_dwordx4 v[148:151], v[66:67], off offset:32
	global_load_dwordx4 v[56:59], v[66:67], off offset:64
	global_load_dwordx4 v[152:155], v[66:67], off offset:96
	s_mov_b32 s0, 0x800000
	v_mov_b32_e32 v218, v181
	s_waitcnt vmcnt(24)
	v_max_f32_e64 v66, |v65|, |v65|
	v_max_f32_e64 v67, |v64|, |v64|
	s_waitcnt vmcnt(22)
	v_mov_b32_e32 v64, v74
	v_max_f32_e32 v74, v67, v66
	s_waitcnt vmcnt(20)
	v_mov_b32_e32 v65, v18
	v_mov_b32_e32 v18, v75
	ds_bpermute_b32 v75, v76, v74
	v_mov_b32_e32 v82, v70
	v_mov_b32_e32 v66, v72
	v_mov_b32_e32 v89, v20
	v_mov_b32_e32 v88, v68
	s_waitcnt lgkmcnt(0)
	v_max_f32_e32 v70, v75, v75
	v_max_f32_e32 v70, v74, v70
	ds_bpermute_b32 v72, v77, v70
	v_mov_b32_e32 v67, v16
	v_mov_b32_e32 v16, v73
	v_mov_b32_e32 v83, v22
	v_mov_b32_e32 v22, v71
	s_waitcnt lgkmcnt(0)
	v_max_f32_e32 v20, v72, v72
	v_max_f32_e32 v20, v70, v20
	ds_bpermute_b32 v68, v78, v20
	s_waitcnt vmcnt(17)
	v_mov_b32_e32 v169, v46
	s_waitcnt lgkmcnt(0)
	v_max_f32_e32 v68, v68, v68
	v_max_f32_e32 v20, v20, v68
	ds_bpermute_b32 v68, v90, v20
	s_waitcnt vmcnt(16)
	v_mov_b32_e32 v167, v40
	s_waitcnt vmcnt(15)
	v_mov_b32_e32 v163, v36
	s_waitcnt vmcnt(11)
	v_and_b32_e32 v114, 0xffff0000, v129
	v_and_b32_e32 v118, 0xffff0000, v128
	s_waitcnt lgkmcnt(0)
	v_max_f32_e32 v68, v68, v68
	v_max_f32_e32 v20, v20, v68
	ds_bpermute_b32 v68, v102, v20
	v_and_b32_e32 v78, 0xffff0000, v97
	v_and_b32_e32 v84, 0xffff0000, v96
	v_lshlrev_b32_e32 v80, 16, v97
	v_lshlrev_b32_e32 v86, 16, v96
	s_waitcnt lgkmcnt(0)
	v_max_f32_e32 v68, v68, v68
	v_max_f32_e32 v20, v20, v68
	ds_bpermute_b32 v68, v108, v20
	v_mov_b32_e32 v72, v78
	v_mov_b32_e32 v73, v84
	v_and_b32_e32 v90, 0xffff0000, v95
	v_mov_b32_e32 v70, v80
	v_mov_b32_e32 v71, v86
	v_pk_mul_f32 v[72:73], v[72:73], v[72:73]
	v_and_b32_e32 v108, 0xffff0000, v94
	v_lshlrev_b32_e32 v92, 16, v95
	v_lshlrev_b32_e32 v102, 16, v94
	v_pk_fma_f32 v[96:97], v[70:71], v[70:71], v[72:73]
	v_mov_b32_e32 v72, v90
	v_mov_b32_e32 v73, v108
	s_waitcnt lgkmcnt(0)
	v_max_f32_e32 v68, v68, v68
	v_mov_b32_e32 v70, v92
	v_mov_b32_e32 v71, v102
	v_pk_mul_f32 v[72:73], v[72:73], v[72:73]
	v_max_f32_e32 v135, v20, v68
	v_pk_fma_f32 v[94:95], v[70:71], v[70:71], v[72:73]
	v_lshlrev_b32_e32 v112, 16, v129
	v_lshlrev_b32_e32 v68, 16, v128
	v_mov_b32_e32 v72, v114
	v_mov_b32_e32 v73, v118
	v_mov_b32_e32 v70, v112
	v_mov_b32_e32 v71, v68
	v_pk_mul_f32 v[72:73], v[72:73], v[72:73]
	s_waitcnt vmcnt(10)
	v_and_b32_e32 v131, 0xffff0000, v137
	v_and_b32_e32 v130, 0xffff0000, v127
	s_waitcnt vmcnt(6)
	v_mov_b32_e32 v40, v61
	s_waitcnt vmcnt(3)
	v_lshlrev_b32_e32 v61, 16, v53
	v_and_b32_e32 v171, 0xffff0000, v53
	s_waitcnt vmcnt(1)
	v_and_b32_e32 v170, 0xffff0000, v57
	v_lshlrev_b32_e32 v173, 16, v52
	v_and_b32_e32 v53, 0xffff0000, v52
	v_and_b32_e32 v52, 0xffff0000, v56
	v_lshlrev_b32_e32 v93, 16, v99
	v_and_b32_e32 v91, 0xffff0000, v99
	v_lshlrev_b32_e32 v103, 16, v98
	v_and_b32_e32 v109, 0xffff0000, v98
	v_pk_fma_f32 v[98:99], v[70:71], v[70:71], v[72:73]
	v_lshlrev_b32_e32 v71, 16, v137
	v_lshlrev_b32_e32 v70, 16, v127
	v_pk_mul_f32 v[74:75], v[130:131], v[130:131]
	v_mov_b32_e32 v158, v144
	s_waitcnt vmcnt(0)
	v_lshlrev_b32_e32 v144, 16, v153
	v_and_b32_e32 v160, 0xffff0000, v153
	v_mov_b32_e32 v36, v141
	v_lshlrev_b32_e32 v141, 16, v55
	v_mov_b32_e32 v153, v42
	v_and_b32_e32 v165, 0xffff0000, v55
	v_mov_b32_e32 v42, v63
	v_lshlrev_b32_e32 v63, 16, v54
	v_mov_b32_e32 v166, v60
	v_and_b32_e32 v55, 0xffff0000, v54
	v_and_b32_e32 v54, 0xffff0000, v58
	v_lshlrev_b32_e32 v60, 16, v57
	v_pk_mul_f32 v[128:129], v[170:171], v[170:171]
	v_lshlrev_b32_e32 v172, 16, v56
	v_pk_mul_f32 v[56:57], v[52:53], v[52:53]
	v_lshlrev_b32_e32 v81, 16, v101
	v_and_b32_e32 v79, 0xffff0000, v101
	v_lshlrev_b32_e32 v87, 16, v100
	v_and_b32_e32 v85, 0xffff0000, v100
	v_mov_b32_e32 v20, v69
	v_lshlrev_b32_e32 v113, 16, v139
	v_and_b32_e32 v115, 0xffff0000, v139
	v_lshlrev_b32_e32 v69, 16, v138
	v_and_b32_e32 v119, 0xffff0000, v138
	v_pk_fma_f32 v[100:101], v[70:71], v[70:71], v[74:75]
	v_lshlrev_b32_e32 v75, 16, v136
	v_and_b32_e32 v133, 0xffff0000, v136
	v_lshlrev_b32_e32 v137, 16, v151
	v_lshlrev_b32_e32 v136, 16, v155
	v_mov_b32_e32 v138, v146
	v_mov_b32_e32 v139, v34
	v_and_b32_e32 v157, 0xffff0000, v151
	v_and_b32_e32 v156, 0xffff0000, v155
	v_mov_b32_e32 v34, v147
	v_lshlrev_b32_e32 v147, 16, v150
	v_lshlrev_b32_e32 v146, 16, v154
	v_mov_b32_e32 v159, v32
	v_and_b32_e32 v151, 0xffff0000, v150
	v_and_b32_e32 v150, 0xffff0000, v154
	v_mov_b32_e32 v32, v145
	v_lshlrev_b32_e32 v145, 16, v149
	v_mov_b32_e32 v154, v142
	v_mov_b32_e32 v155, v38
	v_and_b32_e32 v161, 0xffff0000, v149
	v_mov_b32_e32 v38, v143
	v_lshlrev_b32_e32 v143, 16, v148
	v_lshlrev_b32_e32 v142, 16, v152
	v_mov_b32_e32 v162, v140
	v_and_b32_e32 v149, 0xffff0000, v148
	v_and_b32_e32 v148, 0xffff0000, v152
	v_lshlrev_b32_e32 v140, 16, v59
	v_mov_b32_e32 v152, v62
	v_and_b32_e32 v164, 0xffff0000, v59
	v_lshlrev_b32_e32 v62, 16, v58
	v_pk_mul_f32 v[58:59], v[54:55], v[54:55]
	v_pk_fma_f32 v[128:129], v[60:61], v[60:61], v[128:129]
	v_pk_fma_f32 v[56:57], v[172:173], v[172:173], v[56:57]
	v_lshlrev_b32_e32 v74, 16, v126
	v_and_b32_e32 v132, 0xffff0000, v126
	v_pk_mul_f32 v[126:127], v[164:165], v[164:165]
	v_pk_fma_f32 v[58:59], v[62:63], v[62:63], v[58:59]
	v_add_f32_e32 v46, v57, v129
	v_mov_b32_e32 v116, v124
	v_mov_b32_e32 v117, v26
	v_mov_b32_e32 v26, v125
	v_pk_mul_f32 v[124:125], v[148:149], v[148:149]
	v_pk_fma_f32 v[126:127], v[140:141], v[140:141], v[126:127]
	v_add_f32_e32 v46, v59, v46
	v_mov_b32_e32 v120, v122
	v_mov_b32_e32 v121, v24
	v_mov_b32_e32 v24, v123
	v_pk_mul_f32 v[122:123], v[160:161], v[160:161]
	v_pk_fma_f32 v[124:125], v[142:143], v[142:143], v[124:125]
	v_add_f32_e32 v46, v127, v46
	v_pk_mul_f32 v[110:111], v[150:151], v[150:151]
	v_pk_fma_f32 v[122:123], v[144:145], v[144:145], v[122:123]
	v_add_f32_e32 v46, v125, v46
	v_mov_b32_e32 v76, v104
	v_mov_b32_e32 v77, v28
	v_mov_b32_e32 v28, v105
	v_pk_mul_f32 v[104:105], v[156:157], v[156:157]
	v_pk_fma_f32 v[110:111], v[146:147], v[146:147], v[110:111]
	v_add_f32_e32 v46, v123, v46
	v_pk_fma_f32 v[104:105], v[136:137], v[136:137], v[104:105]
	v_add_f32_e32 v46, v111, v46
	v_add_f32_e32 v46, v105, v46
	v_pk_add_f32 v[56:57], v[56:57], v[46:47] op_sel_hi:[1,0]
	v_mov_b32_e32 v72, v106
	v_pk_add_f32 v[56:57], v[128:129], v[56:57]
	v_mov_b32_e32 v73, v30
	v_pk_add_f32 v[56:57], v[58:59], v[56:57]
	v_mov_b32_e32 v30, v107
	v_pk_add_f32 v[56:57], v[126:127], v[56:57]
	v_pk_mul_f32 v[106:107], v[132:133], v[132:133]
	v_pk_add_f32 v[56:57], v[124:125], v[56:57]
	v_pk_fma_f32 v[106:107], v[74:75], v[74:75], v[106:107]
	v_pk_add_f32 v[56:57], v[122:123], v[56:57]
	v_mul_f32_e32 v46, v69, v69
	v_pk_add_f32 v[56:57], v[110:111], v[56:57]
	v_fmac_f32_e32 v46, v119, v119
	v_pk_add_f32 v[56:57], v[104:105], v[56:57]
	v_mov_b32_e32 v168, v50
	v_pk_add_f32 v[56:57], v[106:107], v[56:57] op_sel:[1,0] op_sel_hi:[0,1]
	v_pk_add_f32 v[56:57], v[100:101], v[56:57] op_sel:[1,0] op_sel_hi:[0,1]
	v_pk_add_f32 v[56:57], v[46:47], v[56:57] op_sel_hi:[0,1]
	v_mul_f32_e32 v46, v113, v113
	v_fmac_f32_e32 v46, v115, v115
	v_pk_add_f32 v[56:57], v[46:47], v[56:57] op_sel_hi:[0,1]
	v_mul_f32_e32 v46, v103, v103
	v_fmac_f32_e32 v46, v109, v109
	v_pk_add_f32 v[56:57], v[46:47], v[56:57] op_sel_hi:[0,1]
	v_mul_f32_e32 v46, v93, v93
	v_fmac_f32_e32 v46, v91, v91
	v_pk_add_f32 v[56:57], v[46:47], v[56:57] op_sel_hi:[0,1]
	v_mul_f32_e32 v46, v87, v87
	v_fmac_f32_e32 v46, v85, v85
	v_pk_add_f32 v[56:57], v[46:47], v[56:57] op_sel_hi:[0,1]
	v_mul_f32_e32 v46, v81, v81
	v_fmac_f32_e32 v46, v79, v79
	v_pk_add_f32 v[56:57], v[46:47], v[56:57] op_sel_hi:[0,1]
	v_pk_add_f32 v[56:57], v[106:107], v[56:57]
	s_nop 0
	v_pk_add_f32 v[56:57], v[100:101], v[56:57]
	s_nop 0
	v_pk_add_f32 v[56:57], v[98:99], v[56:57] op_sel:[1,0] op_sel_hi:[0,1]
	v_pk_add_f32 v[56:57], v[98:99], v[56:57]
	s_nop 0
	v_pk_add_f32 v[56:57], v[94:95], v[56:57] op_sel:[1,0] op_sel_hi:[0,1]
	v_pk_add_f32 v[56:57], v[94:95], v[56:57]
	s_nop 0
	v_pk_add_f32 v[56:57], v[96:97], v[56:57] op_sel:[1,0] op_sel_hi:[0,1]
	v_pk_add_f32 v[56:57], v[96:97], v[56:57]
	s_nop 0
	v_mov_b32_e32 v46, v56
	s_nop 1
	v_permlane32_swap_b32_e32 v56, v46
	v_add_f32_e32 v46, v56, v46
	v_fmamk_f32 v46, v46, 0x3c000000, v208
	v_mul_f32_e32 v50, 0x4b800000, v46
	v_cmp_gt_f32_e64 s[0:1], s0, v46
	s_nop 1
	v_cndmask_b32_e64 v46, v46, v50, s[0:1]
	v_rsq_f32_e32 v56, v46
	v_mov_b32_e32 v46, v51
	v_mov_b32_e32 v51, v44
	v_mov_b32_e32 v50, v48
	v_mul_f32_e32 v44, 0x45800000, v56
	v_cndmask_b32_e64 v174, v56, v44, s[0:1]
	v_pk_mul_f32 v[40:41], v[174:175], v[40:41] op_sel_hi:[0,1]
	v_pk_mul_f32 v[36:37], v[174:175], v[36:37] op_sel_hi:[0,1]
	v_pk_mul_f32 v[106:107], v[40:41], v[54:55]
	v_pk_mul_f32 v[40:41], v[174:175], v[152:153] op_sel_hi:[0,1]
	v_pk_mul_f32 v[96:97], v[36:37], v[148:149]
	v_pk_mul_f32 v[36:37], v[174:175], v[154:155] op_sel_hi:[0,1]
	v_pk_mul_f32 v[50:51], v[174:175], v[50:51] op_sel_hi:[0,1]
	v_mov_b32_e32 v44, v49
	v_pk_mul_f32 v[104:105], v[40:41], v[140:141]
	v_pk_mul_f32 v[40:41], v[174:175], v[42:43] op_sel_hi:[0,1]
	v_pk_mul_f32 v[94:95], v[36:37], v[144:145]
	v_pk_mul_f32 v[36:37], v[174:175], v[38:39] op_sel_hi:[0,1]
	v_pk_mul_f32 v[32:33], v[174:175], v[32:33] op_sel_hi:[0,1]
	v_pk_mul_f32 v[128:129], v[50:51], v[172:173]
	v_pk_mul_f32 v[44:45], v[174:175], v[44:45] op_sel_hi:[0,1]
	v_pk_mul_f32 v[100:101], v[40:41], v[164:165]
	v_pk_mul_f32 v[40:41], v[174:175], v[162:163] op_sel_hi:[0,1]
	v_pk_mul_f32 v[42:43], v[36:37], v[160:161]
	v_pk_mul_f32 v[36:37], v[174:175], v[158:159] op_sel_hi:[0,1]
	v_pk_mul_f32 v[38:39], v[32:33], v[150:151]
	v_pk_mul_f32 v[32:33], v[174:175], v[138:139] op_sel_hi:[0,1]
	v_pk_mul_f32 v[126:127], v[44:45], v[52:53]
	v_pk_mul_f32 v[44:45], v[174:175], v[168:169] op_sel_hi:[0,1]
	v_pk_mul_f32 v[98:99], v[40:41], v[142:143]
	v_pk_mul_f32 v[40:41], v[36:37], v[146:147]
	v_pk_mul_f32 v[36:37], v[32:33], v[136:137]
	v_pk_mul_f32 v[32:33], v[174:175], v[34:35] op_sel_hi:[0,1]
	v_mul_f32_e32 v34, v129, v129
	v_pk_mul_f32 v[124:125], v[44:45], v[60:61]
	v_pk_mul_f32 v[44:45], v[174:175], v[46:47] op_sel_hi:[0,1]
	v_fmac_f32_e32 v34, v127, v127
	v_pk_mul_f32 v[122:123], v[44:45], v[170:171]
	v_pk_mul_f32 v[44:45], v[174:175], v[166:167] op_sel_hi:[0,1]
	v_fmac_f32_e32 v34, v125, v125
	v_pk_mul_f32 v[110:111], v[44:45], v[62:63]
	v_fmac_f32_e32 v34, v123, v123
	v_fmac_f32_e32 v34, v111, v111
	v_fmac_f32_e32 v34, v107, v107
	v_fmac_f32_e32 v34, v105, v105
	v_fmac_f32_e32 v34, v101, v101
	v_fmac_f32_e32 v34, v99, v99
	v_fmac_f32_e32 v34, v97, v97
	v_fmac_f32_e32 v34, v95, v95
	v_fmac_f32_e32 v34, v43, v43
	v_fmac_f32_e32 v34, v41, v41
	v_fmac_f32_e32 v34, v39, v39
	v_pk_mul_f32 v[32:33], v[32:33], v[156:157]
	v_fmac_f32_e32 v34, v37, v37
	v_fmac_f32_e32 v34, v33, v33
	v_pk_fma_f32 v[34:35], v[128:129], v[128:129], v[34:35] op_sel_hi:[1,1,0]
	v_pk_mul_f32 v[44:45], v[174:175], v[76:77] op_sel_hi:[0,1]
	v_pk_fma_f32 v[34:35], v[126:127], v[126:127], v[34:35]
	v_pk_mul_f32 v[76:77], v[44:45], v[74:75]
	v_pk_fma_f32 v[34:35], v[124:125], v[124:125], v[34:35]
	v_pk_mul_f32 v[28:29], v[174:175], v[28:29] op_sel_hi:[0,1]
	v_pk_fma_f32 v[34:35], v[122:123], v[122:123], v[34:35]
	v_mul_f32_e32 v44, v77, v77
	v_pk_fma_f32 v[34:35], v[110:111], v[110:111], v[34:35]
	v_pk_mul_f32 v[74:75], v[28:29], v[132:133]
	v_pk_fma_f32 v[34:35], v[106:107], v[106:107], v[34:35]
	v_mul_f32_e32 v28, v75, v75
	v_pk_fma_f32 v[34:35], v[104:105], v[104:105], v[34:35]
	v_pk_mul_f32 v[30:31], v[174:175], v[30:31] op_sel_hi:[0,1]
	v_pk_fma_f32 v[34:35], v[100:101], v[100:101], v[34:35]
	v_pk_mul_f32 v[24:25], v[174:175], v[24:25] op_sel_hi:[0,1]
	v_pk_fma_f32 v[34:35], v[98:99], v[98:99], v[34:35]
	v_pk_mul_f32 v[62:63], v[24:25], v[118:119]
	v_pk_fma_f32 v[34:35], v[96:97], v[96:97], v[34:35]
	v_mul_f32_e32 v24, v63, v63
	v_pk_fma_f32 v[34:35], v[94:95], v[94:95], v[34:35]
	v_pk_mul_f32 v[26:27], v[174:175], v[26:27] op_sel_hi:[0,1]
	v_pk_fma_f32 v[34:35], v[42:43], v[42:43], v[34:35]
	v_pk_mul_f32 v[58:59], v[26:27], v[114:115]
	v_pk_fma_f32 v[34:35], v[40:41], v[40:41], v[34:35]
	v_mul_f32_e32 v26, v59, v59
	v_pk_fma_f32 v[34:35], v[38:39], v[38:39], v[34:35]
	v_pk_mul_f32 v[20:21], v[174:175], v[20:21] op_sel_hi:[0,1]
	v_pk_fma_f32 v[34:35], v[36:37], v[36:37], v[34:35]
	v_pk_mul_f32 v[54:55], v[20:21], v[108:109]
	v_pk_fma_f32 v[34:35], v[32:33], v[32:33], v[34:35]
	v_mul_f32_e32 v20, v55, v55
	v_pk_add_f32 v[34:35], v[44:45], v[34:35] op_sel_hi:[0,1]
	v_pk_add_f32 v[28:29], v[28:29], v[34:35] op_sel_hi:[0,1]
	v_pk_mul_f32 v[34:35], v[174:175], v[72:73] op_sel_hi:[0,1]
	v_pk_mul_f32 v[72:73], v[34:35], v[70:71]
	v_pk_mul_f32 v[70:71], v[30:31], v[130:131]
	v_mul_f32_e32 v34, v73, v73
	v_pk_add_f32 v[28:29], v[34:35], v[28:29] op_sel_hi:[0,1]
	v_mul_f32_e32 v30, v71, v71
	v_pk_add_f32 v[28:29], v[30:31], v[28:29] op_sel_hi:[0,1]
	v_pk_mul_f32 v[30:31], v[174:175], v[120:121] op_sel_hi:[0,1]
	v_pk_mul_f32 v[68:69], v[30:31], v[68:69]
	v_pk_mul_f32 v[22:23], v[174:175], v[22:23] op_sel_hi:[0,1]
	v_mul_f32_e32 v30, v69, v69
	v_pk_add_f32 v[28:29], v[30:31], v[28:29] op_sel_hi:[0,1]
	v_pk_add_f32 v[24:25], v[24:25], v[28:29] op_sel_hi:[0,1]
	v_pk_mul_f32 v[28:29], v[174:175], v[116:117] op_sel_hi:[0,1]
	v_pk_mul_f32 v[60:61], v[28:29], v[112:113]
	v_pk_mul_f32 v[50:51], v[22:23], v[90:91]
	v_mul_f32_e32 v28, v61, v61
	v_pk_add_f32 v[24:25], v[28:29], v[24:25] op_sel_hi:[0,1]
	v_pk_add_f32 v[24:25], v[26:27], v[24:25] op_sel_hi:[0,1]
	v_pk_mul_f32 v[26:27], v[174:175], v[88:89] op_sel_hi:[0,1]
	v_pk_mul_f32 v[56:57], v[26:27], v[102:103]
	v_mul_f32_e32 v22, v51, v51
	v_mul_f32_e32 v26, v57, v57
	v_pk_add_f32 v[24:25], v[26:27], v[24:25] op_sel_hi:[0,1]
	v_pk_add_f32 v[20:21], v[20:21], v[24:25] op_sel_hi:[0,1]
	v_pk_mul_f32 v[24:25], v[174:175], v[82:83] op_sel_hi:[0,1]
	v_pk_mul_f32 v[52:53], v[24:25], v[92:93]
	v_pk_mul_f32 v[16:17], v[174:175], v[16:17] op_sel_hi:[0,1]
	v_mul_f32_e32 v24, v53, v53
	v_pk_add_f32 v[20:21], v[24:25], v[20:21] op_sel_hi:[0,1]
	v_pk_add_f32 v[20:21], v[22:23], v[20:21] op_sel_hi:[0,1]
	v_pk_mul_f32 v[22:23], v[174:175], v[66:67] op_sel_hi:[0,1]
	v_pk_mul_f32 v[48:49], v[22:23], v[86:87]
	v_pk_mul_f32 v[46:47], v[16:17], v[84:85]
	v_mul_f32_e32 v22, v49, v49
	v_pk_add_f32 v[20:21], v[22:23], v[20:21] op_sel_hi:[0,1]
	v_mul_f32_e32 v16, v47, v47
	v_pk_add_f32 v[16:17], v[16:17], v[20:21] op_sel_hi:[0,1]
	v_pk_mul_f32 v[20:21], v[174:175], v[64:65] op_sel_hi:[0,1]
	v_pk_mul_f32 v[44:45], v[20:21], v[80:81]
	v_pk_mul_f32 v[18:19], v[174:175], v[18:19] op_sel_hi:[0,1]
	v_mul_f32_e32 v20, v45, v45
	v_pk_mul_f32 v[34:35], v[18:19], v[78:79]
	v_pk_add_f32 v[16:17], v[20:21], v[16:17] op_sel_hi:[0,1]
	v_mul_f32_e32 v18, v35, v35
	v_pk_add_f32 v[16:17], v[18:19], v[16:17] op_sel_hi:[0,1]
	v_pk_fma_f32 v[16:17], v[76:77], v[76:77], v[16:17]
	s_mov_b32 s0, 0xf800000
	v_pk_fma_f32 v[16:17], v[74:75], v[74:75], v[16:17]
	v_add_u32_e32 v108, s8, v134
	v_pk_fma_f32 v[16:17], v[72:73], v[72:73], v[16:17]
	v_and_or_b32 v180, v108, s4, v200
	v_pk_fma_f32 v[16:17], v[70:71], v[70:71], v[16:17]
	v_lshl_add_u64 v[102:103], v[180:181], 2, s[6:7]
	v_pk_fma_f32 v[16:17], v[68:69], v[68:69], v[16:17]
	v_lshlrev_b32_e32 v108, 6, v108
	v_pk_fma_f32 v[16:17], v[62:63], v[62:63], v[16:17]
	s_nop 0
	v_pk_fma_f32 v[16:17], v[60:61], v[60:61], v[16:17]
	s_nop 0
	v_pk_fma_f32 v[16:17], v[58:59], v[58:59], v[16:17]
	s_nop 0
	v_pk_fma_f32 v[16:17], v[56:57], v[56:57], v[16:17]
	s_nop 0
	v_pk_fma_f32 v[16:17], v[54:55], v[54:55], v[16:17]
	s_nop 0
	v_pk_fma_f32 v[16:17], v[52:53], v[52:53], v[16:17]
	s_nop 0
	v_pk_fma_f32 v[16:17], v[50:51], v[50:51], v[16:17]
	s_nop 0
	v_pk_fma_f32 v[16:17], v[48:49], v[48:49], v[16:17]
	s_nop 0
	v_pk_fma_f32 v[16:17], v[46:47], v[46:47], v[16:17]
	s_nop 0
	v_pk_fma_f32 v[16:17], v[44:45], v[44:45], v[16:17]
	s_nop 0
	v_pk_fma_f32 v[16:17], v[34:35], v[34:35], v[16:17]
	s_nop 0
	v_mov_b32_e32 v17, v16
	s_nop 1
	v_permlane32_swap_b32_e32 v16, v17
	v_add_f32_e32 v16, v16, v17
	v_mul_f32_e32 v17, 0x4f800000, v16
	v_cmp_gt_f32_e64 s[0:1], s0, v16
	s_nop 1
	v_cndmask_b32_e64 v16, v16, v17, s[0:1]
	v_sqrt_f32_e32 v17, v16
	s_nop 0
	v_add_u32_e32 v18, -1, v17
	v_fma_f32 v19, -v18, v17, v16
	v_cmp_ge_f32_e64 s[4:5], 0, v19
	v_add_u32_e32 v19, 1, v17
	s_nop 0
	v_cndmask_b32_e64 v18, v17, v18, s[4:5]
	v_fma_f32 v17, -v19, v17, v16
	v_cmp_lt_f32_e64 s[4:5], 0, v17
	s_nop 1
	v_cndmask_b32_e64 v17, v18, v19, s[4:5]
	v_mul_f32_e32 v18, 0x37800000, v17
	v_cndmask_b32_e64 v17, v17, v18, s[0:1]
	v_cmp_class_f32_e64 s[0:1], v16, v209
	s_movk_i32 s4, 0x4000
	s_nop 0
	v_cndmask_b32_e64 v16, v17, v16, s[0:1]
	v_mul_f32_e32 v16, 0x3e0293ee, v16
	v_mul_f32_e32 v16, 0xc13504f3, v16
	v_mul_f32_e32 v16, v16, v135
	v_mul_f32_e32 v16, 0x3f801062, v16
	v_max_f32_e32 v16, 0xc2700000, v16
	v_mov_b32_e32 v17, v16
	v_mov_b32_e32 v18, v16
	v_mov_b32_e32 v19, v16
	v_mov_b32_e32 v20, v16
	v_mov_b32_e32 v21, v16
	v_mov_b32_e32 v22, v16
	v_mov_b32_e32 v23, v16
	v_mov_b32_e32 v24, v16
	v_mov_b32_e32 v25, v16
	v_mov_b32_e32 v26, v16
	v_mov_b32_e32 v27, v16
	v_mov_b32_e32 v28, v16
	v_mov_b32_e32 v29, v16
	v_mov_b32_e32 v30, v16
	v_mov_b32_e32 v31, v16
	global_load_dwordx4 v[64:67], v[102:103], off
	global_load_dwordx4 v[78:81], v[102:103], off offset:16
	global_load_dwordx4 v[82:85], v[102:103], off offset:32
	global_load_dwordx4 v[86:89], v[102:103], off offset:48
	global_load_dwordx4 v[90:93], v[102:103], off offset:128
	global_load_dwordx4 v[112:115], v[102:103], off offset:144
	global_load_dwordx4 v[116:119], v[102:103], off offset:176
	global_load_dwordx4 v[130:133], v[102:103], off offset:160
	s_movk_i32 s0, 0xfc0
	v_and_or_b32 v108, v108, s0, v200
	v_lshlrev_b32_e32 v108, 2, v108
	s_lshr_b32 s0, s97, 3
	s_and_b32 s0, s0, 0x1ffffff0
	s_waitcnt vmcnt(7)
	v_pk_mul_f32 v[102:103], v[128:129], v[64:65] op_sel:[1,0] op_sel_hi:[0,1]
	v_pk_mul_f32 v[64:65], v[128:129], v[64:65]
	v_sub_f32_e32 v102, v102, v103
	v_add_f32_e32 v64, v64, v65
	v_mul_f32_e32 v120, 0x3e0293ee, v64
	v_pk_mul_f32 v[64:65], v[126:127], v[66:67] op_sel:[1,0] op_sel_hi:[0,1]
	v_sub_f32_e32 v64, v64, v65
	v_mul_f32_e32 v121, 0x3e0293ee, v64
	v_pk_mul_f32 v[64:65], v[126:127], v[66:67]
	v_mul_f32_e32 v109, 0x3e0293ee, v102
	v_add_f32_e32 v64, v64, v65
	v_mul_f32_e32 v126, 0x3e0293ee, v64
	s_waitcnt vmcnt(6)
	v_pk_mul_f32 v[64:65], v[124:125], v[78:79] op_sel:[1,0] op_sel_hi:[0,1]
	v_sub_f32_e32 v64, v64, v65
	v_mul_f32_e32 v127, 0x3e0293ee, v64
	v_pk_mul_f32 v[64:65], v[124:125], v[78:79]
	s_nop 0
	v_add_f32_e32 v64, v64, v65
	v_mul_f32_e32 v124, 0x3e0293ee, v64
	v_pk_mul_f32 v[64:65], v[122:123], v[80:81] op_sel:[1,0] op_sel_hi:[0,1]
	v_sub_f32_e32 v64, v64, v65
	v_mul_f32_e32 v125, 0x3e0293ee, v64
	v_pk_mul_f32 v[64:65], v[122:123], v[80:81]
	s_nop 0
	v_add_f32_e32 v102, v64, v65
	global_load_dwordx4 v[64:67], v108, s[6:7] offset:16
	global_load_dwordx4 v[78:81], v108, s[6:7]
	v_mul_f32_e32 v122, 0x3e0293ee, v102
	s_waitcnt vmcnt(7)
	v_pk_mul_f32 v[102:103], v[110:111], v[82:83] op_sel:[1,0] op_sel_hi:[0,1]
	v_pk_mul_f32 v[82:83], v[110:111], v[82:83]
	v_sub_f32_e32 v102, v102, v103
	v_add_f32_e32 v82, v82, v83
	v_mul_f32_e32 v110, 0x3e0293ee, v82
	v_pk_mul_f32 v[82:83], v[106:107], v[84:85] op_sel:[1,0] op_sel_hi:[0,1]
	v_sub_f32_e32 v82, v82, v83
	v_mul_f32_e32 v111, 0x3e0293ee, v82
	v_pk_mul_f32 v[82:83], v[106:107], v[84:85]
	v_mul_f32_e32 v123, 0x3e0293ee, v102
	v_add_f32_e32 v82, v82, v83
	v_mul_f32_e32 v106, 0x3e0293ee, v82
	s_waitcnt vmcnt(6)
	v_pk_mul_f32 v[82:83], v[104:105], v[86:87] op_sel:[1,0] op_sel_hi:[0,1]
	v_sub_f32_e32 v82, v82, v83
	v_mul_f32_e32 v107, 0x3e0293ee, v82
	v_pk_mul_f32 v[82:83], v[104:105], v[86:87]
	v_pk_mul_f32 v[86:87], v[100:101], v[88:89]
	v_add_f32_e32 v82, v82, v83
	v_mul_f32_e32 v128, 0x3e0293ee, v82
	v_pk_mul_f32 v[82:83], v[100:101], v[88:89] op_sel:[1,0] op_sel_hi:[0,1]
	v_sub_f32_e32 v82, v82, v83
	v_mul_f32_e32 v129, 0x3e0293ee, v82
	global_load_dwordx4 v[82:85], v108, s[6:7] offset:48
	global_load_dwordx4 v[102:105], v108, s[6:7] offset:32
	v_add_f32_e32 v86, v86, v87
	v_mul_f32_e32 v100, 0x3e0293ee, v86
	s_waitcnt vmcnt(7)
	v_pk_mul_f32 v[86:87], v[98:99], v[90:91] op_sel:[1,0] op_sel_hi:[0,1]
	v_sub_f32_e32 v86, v86, v87
	v_mul_f32_e32 v101, 0x3e0293ee, v86
	v_pk_mul_f32 v[86:87], v[98:99], v[90:91]
	s_nop 0
	v_add_f32_e32 v86, v86, v87
	v_mul_f32_e32 v98, 0x3e0293ee, v86
	v_pk_mul_f32 v[86:87], v[96:97], v[92:93] op_sel:[1,0] op_sel_hi:[0,1]
	v_sub_f32_e32 v86, v86, v87
	v_mul_f32_e32 v99, 0x3e0293ee, v86
	v_pk_mul_f32 v[86:87], v[96:97], v[92:93]
	s_nop 0
	v_add_f32_e32 v86, v86, v87
	v_mul_f32_e32 v96, 0x3e0293ee, v86
	s_waitcnt vmcnt(6)
	v_pk_mul_f32 v[86:87], v[94:95], v[112:113] op_sel:[1,0] op_sel_hi:[0,1]
	v_sub_f32_e32 v86, v86, v87
	v_mul_f32_e32 v97, 0x3e0293ee, v86
	v_pk_mul_f32 v[86:87], v[94:95], v[112:113]
	v_pk_mul_f32 v[94:95], v[42:43], v[114:115] op_sel:[1,0] op_sel_hi:[0,1]
	v_add_f32_e32 v86, v86, v87
	v_mul_f32_e32 v112, 0x3e0293ee, v86
	global_load_dwordx4 v[86:89], v108, s[6:7] offset:144
	global_load_dwordx4 v[90:93], v108, s[6:7] offset:128
	v_pk_mul_f32 v[42:43], v[42:43], v[114:115]
	v_sub_f32_e32 v94, v94, v95
	v_add_f32_e32 v42, v42, v43
	v_mul_f32_e32 v114, 0x3e0293ee, v42
	s_waitcnt vmcnt(6)
	v_pk_mul_f32 v[42:43], v[40:41], v[130:131] op_sel:[1,0] op_sel_hi:[0,1]
	v_pk_mul_f32 v[40:41], v[40:41], v[130:131]
	v_sub_f32_e32 v42, v42, v43
	v_add_f32_e32 v40, v40, v41
	v_mul_f32_e32 v130, 0x3e0293ee, v40
	v_pk_mul_f32 v[40:41], v[38:39], v[132:133] op_sel:[1,0] op_sel_hi:[0,1]
	v_pk_mul_f32 v[38:39], v[38:39], v[132:133]
	v_sub_f32_e32 v40, v40, v41
	v_add_f32_e32 v38, v38, v39
	v_mul_f32_e32 v132, 0x3e0293ee, v38
	v_pk_mul_f32 v[38:39], v[36:37], v[116:117] op_sel:[1,0] op_sel_hi:[0,1]
	v_sub_f32_e32 v38, v38, v39
	v_pk_mul_f32 v[36:37], v[36:37], v[116:117]
	v_mul_f32_e32 v113, 0x3e0293ee, v94
	v_mul_f32_e32 v115, 0x3e0293ee, v42
	v_mul_f32_e32 v131, 0x3e0293ee, v40
	v_mul_f32_e32 v133, 0x3e0293ee, v38
	v_add_f32_e32 v94, v36, v37
	global_load_dwordx4 v[36:39], v108, s[6:7] offset:176
	global_load_dwordx4 v[40:43], v108, s[6:7] offset:160
	v_mul_f32_e32 v108, 0x3e0293ee, v94
	v_pk_mul_f32 v[94:95], v[32:33], v[118:119] op_sel:[1,0] op_sel_hi:[0,1]
	v_pk_mul_f32 v[32:33], v[32:33], v[118:119]
	v_sub_f32_e32 v94, v94, v95
	v_add_f32_e32 v32, v32, v33
	v_mul_f32_e32 v95, 0x3e0293ee, v32
	v_mul_f32_e32 v94, 0x3e0293ee, v94
	v_cvt_pk_bf16_f32 v172, v109, v121
	s_waitcnt vmcnt(6)
	v_pk_mul_f32 v[32:33], v[76:77], v[78:79] op_sel:[1,0] op_sel_hi:[0,1]
	v_sub_f32_e32 v32, v32, v33
	v_mul_f32_e32 v116, 0x3e0293ee, v32
	v_pk_mul_f32 v[32:33], v[76:77], v[78:79]
	v_cvt_pk_bf16_f32 v173, v127, v125
	v_cvt_pk_bf16_f32 v174, v123, v111
	v_cvt_pk_bf16_f32 v175, v107, v129
	v_cvt_pk_bf16_f32 v168, v101, v99
	v_cvt_pk_bf16_f32 v169, v97, v113
	s_nop 0
	v_add_f32_e32 v32, v32, v33
	v_mul_f32_e32 v76, 0x3e0293ee, v32
	v_pk_mul_f32 v[32:33], v[74:75], v[80:81] op_sel:[1,0] op_sel_hi:[0,1]
	v_sub_f32_e32 v32, v32, v33
	v_mul_f32_e32 v77, 0x3e0293ee, v32
	v_pk_mul_f32 v[32:33], v[74:75], v[80:81]
	v_cvt_pk_bf16_f32 v170, v115, v131
	v_cvt_pk_bf16_f32 v171, v133, v94
	v_cvt_pk_bf16_f32 v164, v120, v126
	v_cvt_pk_bf16_f32 v165, v124, v122
	v_cvt_pk_bf16_f32 v166, v110, v106
	s_nop 0
	v_add_f32_e32 v32, v32, v33
	v_mul_f32_e32 v74, 0x3e0293ee, v32
	v_pk_mul_f32 v[32:33], v[72:73], v[64:65] op_sel:[1,0] op_sel_hi:[0,1]
	v_sub_f32_e32 v32, v32, v33
	v_mul_f32_e32 v75, 0x3e0293ee, v32
	v_pk_mul_f32 v[32:33], v[72:73], v[64:65]
	v_cvt_pk_bf16_f32 v167, v128, v100
	v_cvt_pk_bf16_f32 v160, v98, v96
	v_cvt_pk_bf16_f32 v161, v112, v114
	v_cvt_pk_bf16_f32 v162, v130, v132
	v_cvt_pk_bf16_f32 v163, v108, v95
	s_nop 0
	v_add_f32_e32 v32, v32, v33
	v_mul_f32_e32 v64, 0x3e0293ee, v32
	v_pk_mul_f32 v[32:33], v[70:71], v[66:67] op_sel:[1,0] op_sel_hi:[0,1]
	v_sub_f32_e32 v32, v32, v33
	v_mul_f32_e32 v65, 0x3e0293ee, v32
	v_pk_mul_f32 v[32:33], v[70:71], v[66:67]
	v_cvt_pk_bf16_f32 v156, v116, v77
	v_cvt_pk_bf16_f32 v157, v75, v65
	v_mov_b32_e32 v65, v181
	v_add_f32_e32 v32, v32, v33
	v_mul_f32_e32 v66, 0x3e0293ee, v32
	s_waitcnt vmcnt(4)
	v_pk_mul_f32 v[32:33], v[68:69], v[102:103] op_sel:[1,0] op_sel_hi:[0,1]
	v_sub_f32_e32 v32, v32, v33
	v_mul_f32_e32 v67, 0x3e0293ee, v32
	v_pk_mul_f32 v[32:33], v[68:69], v[102:103]
	v_mov_b32_e32 v70, v181
	v_add_f32_e32 v32, v32, v33
	v_mul_f32_e32 v68, 0x3e0293ee, v32
	v_pk_mul_f32 v[32:33], v[62:63], v[104:105] op_sel:[1,0] op_sel_hi:[0,1]
	v_sub_f32_e32 v32, v32, v33
	v_mul_f32_e32 v69, 0x3e0293ee, v32
	v_pk_mul_f32 v[32:33], v[62:63], v[104:105]
	v_cvt_pk_bf16_f32 v158, v67, v69
	v_mov_b32_e32 v67, v181
	v_add_f32_e32 v32, v32, v33
	v_mul_f32_e32 v62, 0x3e0293ee, v32
	v_pk_mul_f32 v[32:33], v[60:61], v[82:83] op_sel:[1,0] op_sel_hi:[0,1]
	v_sub_f32_e32 v32, v32, v33
	v_mul_f32_e32 v63, 0x3e0293ee, v32
	v_pk_mul_f32 v[32:33], v[60:61], v[82:83]
	v_mov_b32_e32 v69, v181
	v_add_f32_e32 v32, v32, v33
	v_mul_f32_e32 v60, 0x3e0293ee, v32
	v_pk_mul_f32 v[32:33], v[58:59], v[84:85] op_sel:[1,0] op_sel_hi:[0,1]
	v_sub_f32_e32 v32, v32, v33
	v_mul_f32_e32 v61, 0x3e0293ee, v32
	v_pk_mul_f32 v[32:33], v[58:59], v[84:85]
	v_cvt_pk_bf16_f32 v159, v63, v61
	v_mov_b32_e32 v61, v181
	v_add_f32_e32 v32, v32, v33
	v_mul_f32_e32 v58, 0x3e0293ee, v32
	s_waitcnt vmcnt(2)
	v_pk_mul_f32 v[32:33], v[56:57], v[90:91] op_sel:[1,0] op_sel_hi:[0,1]
	v_sub_f32_e32 v32, v32, v33
	v_mul_f32_e32 v59, 0x3e0293ee, v32
	v_pk_mul_f32 v[32:33], v[56:57], v[90:91]
	v_mov_b32_e32 v63, v181
	v_add_f32_e32 v32, v32, v33
	v_mul_f32_e32 v56, 0x3e0293ee, v32
	v_pk_mul_f32 v[32:33], v[54:55], v[92:93] op_sel:[1,0] op_sel_hi:[0,1]
	v_sub_f32_e32 v32, v32, v33
	v_mul_f32_e32 v57, 0x3e0293ee, v32
	v_pk_mul_f32 v[32:33], v[54:55], v[92:93]
	v_cvt_pk_bf16_f32 v152, v59, v57
	v_mov_b32_e32 v57, v181
	v_add_f32_e32 v32, v32, v33
	v_mul_f32_e32 v54, 0x3e0293ee, v32
	v_pk_mul_f32 v[32:33], v[52:53], v[86:87] op_sel:[1,0] op_sel_hi:[0,1]
	v_sub_f32_e32 v32, v32, v33
	v_mul_f32_e32 v55, 0x3e0293ee, v32
	v_pk_mul_f32 v[32:33], v[52:53], v[86:87]
	v_mov_b32_e32 v59, v181
	v_add_f32_e32 v32, v32, v33
	v_mul_f32_e32 v52, 0x3e0293ee, v32
	v_pk_mul_f32 v[32:33], v[50:51], v[88:89] op_sel:[1,0] op_sel_hi:[0,1]
	v_sub_f32_e32 v32, v32, v33
	v_mul_f32_e32 v53, 0x3e0293ee, v32
	v_pk_mul_f32 v[32:33], v[50:51], v[88:89]
	v_cvt_pk_bf16_f32 v153, v55, v53
	v_mov_b32_e32 v71, v181
	v_add_f32_e32 v32, v32, v33
	v_mul_f32_e32 v50, 0x3e0293ee, v32
	s_waitcnt vmcnt(0)
	v_pk_mul_f32 v[32:33], v[48:49], v[40:41] op_sel:[1,0] op_sel_hi:[0,1]
	v_sub_f32_e32 v32, v32, v33
	v_mul_f32_e32 v51, 0x3e0293ee, v32
	v_pk_mul_f32 v[32:33], v[48:49], v[40:41]
	v_mov_b32_e32 v72, v181
	v_add_f32_e32 v32, v32, v33
	v_mul_f32_e32 v40, 0x3e0293ee, v32
	v_pk_mul_f32 v[32:33], v[46:47], v[42:43] op_sel:[1,0] op_sel_hi:[0,1]
	v_sub_f32_e32 v32, v32, v33
	v_mul_f32_e32 v41, 0x3e0293ee, v32
	v_pk_mul_f32 v[32:33], v[46:47], v[42:43]
	v_cvt_pk_bf16_f32 v154, v51, v41
	v_mov_b32_e32 v73, v181
	v_add_f32_e32 v32, v32, v33
	v_mul_f32_e32 v42, 0x3e0293ee, v32
	v_pk_mul_f32 v[32:33], v[44:45], v[36:37] op_sel:[1,0] op_sel_hi:[0,1]
	v_sub_f32_e32 v32, v32, v33
	v_mul_f32_e32 v43, 0x3e0293ee, v32
	v_pk_mul_f32 v[32:33], v[44:45], v[36:37]
	v_mov_b32_e32 v75, v181
	v_add_f32_e32 v32, v32, v33
	v_mul_f32_e32 v36, 0x3e0293ee, v32
	v_pk_mul_f32 v[32:33], v[34:35], v[38:39] op_sel:[1,0] op_sel_hi:[0,1]
	v_sub_f32_e32 v32, v32, v33
	v_mul_f32_e32 v37, 0x3e0293ee, v32
	v_pk_mul_f32 v[32:33], v[34:35], v[38:39]
	v_cvt_pk_bf16_f32 v155, v43, v37
	v_cvt_pk_bf16_f32 v148, v76, v74
	v_cvt_pk_bf16_f32 v149, v64, v66
	v_cvt_pk_bf16_f32 v150, v68, v62
	v_cvt_pk_bf16_f32 v151, v60, v58
	s_nop 0
	v_add_f32_e32 v32, v32, v33
	v_mul_f32_e32 v32, 0x3e0293ee, v32
	v_cvt_pk_bf16_f32 v144, v56, v54
	v_cvt_pk_bf16_f32 v145, v52, v50
	v_cvt_pk_bf16_f32 v146, v40, v42
	v_cvt_pk_bf16_f32 v147, v36, v32
	v_and_or_b32 v32, s8, 32, v178
	v_lshl_add_u32 v206, v176, 4, 16
	s_lshr_b32 s0, s97, 3
	s_and_b32 s0, s0, 0x1ffffff0
	v_mov_b32_e32 v33, s0
	v_mad_u32_u24 v32, v32, s82, v33
	v_lshl_or_b32 v32, v179, 3, v32
	v_lshlrev_b32_e32 v180, 1, v32
	s_lshr_b32 s0, s97, 4
	s_and_b32 s5, s0, 0xffffff0
	s_lshr_b32 s0, s97, 5
	v_and_or_b32 v32, s0, 2, v179
	s_lshr_b32 s18, s97, 4
	s_and_b32 s18, s18, 8
	v_bfe_u32 v33, v177, 2, 3
	v_or_b32_e32 v33, s5, v33
	v_or_b32_e32 v33, s18, v33
	v_lshlrev_b32_e32 v32, 5, v32
	v_mul_lo_u32 v33, v33, s82
	v_or3_b32 v32, v32, v204, v33
	v_lshlrev_b32_e32 v199, 1, v32
	v_add_u32_e32 v198, 0x80, v180
	v_add_u32_e32 v219, 0x48000, v199
	s_lshl_b32 s0, s33, 10
	s_add_i32 s74, s0, 16
	s_add_i32 s68, s0, 0x10010
	s_add_i32 m0, s74, 0
	s_nop 0
	global_load_lds_dwordx4 v180, s[72:73]
	s_add_i32 m0, s74, 8192
	s_nop 0
	global_load_lds_dwordx4 v198, s[72:73]
	s_add_u32 s72, s72, 0x90000
	s_addc_u32 s73, s73, 0
	s_add_i32 m0, s74, 16384
	s_nop 0
	global_load_lds_dwordx4 v180, s[72:73]
	s_add_i32 m0, s74, 24576
	s_nop 0
	global_load_lds_dwordx4 v198, s[72:73]
	s_add_u32 s72, s72, 0x90000
	s_addc_u32 s73, s73, 0
	s_add_i32 m0, s68, 0
	s_nop 0
	global_load_lds_dwordx4 v199, s[70:71]
	s_add_i32 m0, s68, 8192
	s_nop 0
	global_load_lds_dwordx4 v219, s[70:71]
	s_add_u32 s70, s70, 0x90000
	s_addc_u32 s71, s71, 0
	s_add_i32 m0, s74, 32768
	s_nop 0
	global_load_lds_dwordx4 v180, s[72:73]
	s_add_i32 m0, s74, 40960
	s_nop 0
	global_load_lds_dwordx4 v198, s[72:73]
	s_add_u32 s72, s72, 0x90000
	s_addc_u32 s73, s73, 0
	s_add_i32 m0, s68, 16384
	s_nop 0
	global_load_lds_dwordx4 v199, s[70:71]
	s_add_i32 m0, s68, 24576
	s_nop 0
	global_load_lds_dwordx4 v219, s[70:71]
	s_add_u32 s70, s70, 0x90000
	s_addc_u32 s71, s71, 0
	s_add_i32 m0, s74, 49152
	s_nop 0
	global_load_lds_dwordx4 v180, s[72:73]
	s_add_i32 m0, s74, 57344
	s_nop 0
	global_load_lds_dwordx4 v198, s[72:73]
	s_add_u32 s72, s72, 0x90000
	s_addc_u32 s73, s73, 0
	s_add_i32 m0, s68, 32768
	s_nop 0
	global_load_lds_dwordx4 v199, s[70:71]
	s_add_i32 m0, s68, 40960
	s_nop 0
	global_load_lds_dwordx4 v219, s[70:71]
	s_add_u32 s70, s70, 0x90000
	s_addc_u32 s71, s71, 0
	v_mov_b32_e32 v80, 0
	v_mov_b32_e32 v81, 0
	v_mov_b32_e32 v82, 0
	v_mov_b32_e32 v83, 0
	v_mov_b32_e32 v84, 0
	v_mov_b32_e32 v85, 0
	v_mov_b32_e32 v86, 0
	v_mov_b32_e32 v87, 0
	v_mov_b32_e32 v88, 0
	v_mov_b32_e32 v89, 0
	v_mov_b32_e32 v90, 0
	v_mov_b32_e32 v91, 0
	v_mov_b32_e32 v92, 0
	v_mov_b32_e32 v93, 0
	v_mov_b32_e32 v94, 0
	v_mov_b32_e32 v95, 0
	v_mov_b32_e32 v64, 0
	v_mov_b32_e32 v65, 0
	v_mov_b32_e32 v66, 0
	v_mov_b32_e32 v67, 0
	v_mov_b32_e32 v68, 0
	v_mov_b32_e32 v69, 0
	v_mov_b32_e32 v70, 0
	v_mov_b32_e32 v71, 0
	v_mov_b32_e32 v72, 0
	v_mov_b32_e32 v73, 0
	v_mov_b32_e32 v74, 0
	v_mov_b32_e32 v75, 0
	v_mov_b32_e32 v76, 0
	v_mov_b32_e32 v77, 0
	v_mov_b32_e32 v78, 0
	v_mov_b32_e32 v79, 0
	v_mov_b32_e32 v48, 0
	v_mov_b32_e32 v49, 0
	v_mov_b32_e32 v50, 0
	v_mov_b32_e32 v51, 0
	v_mov_b32_e32 v52, 0
	v_mov_b32_e32 v53, 0
	v_mov_b32_e32 v54, 0
	v_mov_b32_e32 v55, 0
	v_mov_b32_e32 v56, 0
	v_mov_b32_e32 v57, 0
	v_mov_b32_e32 v58, 0
	v_mov_b32_e32 v59, 0
	v_mov_b32_e32 v60, 0
	v_mov_b32_e32 v61, 0
	v_mov_b32_e32 v62, 0
	v_mov_b32_e32 v63, 0
	v_mov_b32_e32 v32, 0
	v_mov_b32_e32 v33, 0
	v_mov_b32_e32 v34, 0
	v_mov_b32_e32 v35, 0
	v_mov_b32_e32 v36, 0
	v_mov_b32_e32 v37, 0
	v_mov_b32_e32 v38, 0
	v_mov_b32_e32 v39, 0
	v_mov_b32_e32 v40, 0
	v_mov_b32_e32 v41, 0
	v_mov_b32_e32 v42, 0
	v_mov_b32_e32 v43, 0
	v_mov_b32_e32 v44, 0
	v_mov_b32_e32 v45, 0
	v_mov_b32_e32 v46, 0
	v_mov_b32_e32 v47, 0
	v_mov_b32_e32 v218, 0
	v_mov_b32_e32 v248, 0
	v_mov_b32_e32 v249, 0
	v_mov_b32_e32 v251, 0
	s_waitcnt vmcnt(8)
	s_barrier
	ds_read_b128 v[236:239], v206 offset:0
	ds_read_b128 v[240:243], v206 offset:2048
	ds_read_b128 v[244:247], v206 offset:4096
	s_waitcnt lgkmcnt(2)
	v_mfma_f32_32x32x16_bf16 v[96:111], v[236:239], v[172:175], v[16:31]
	ds_read_b128 v[190:193], v206 offset:6144
	s_waitcnt lgkmcnt(2)
	v_mfma_f32_32x32x16_bf16 v[96:111], v[240:243], v[168:171], v[96:111]
	ds_read_b128 v[194:197], v206 offset:8192
	s_waitcnt lgkmcnt(2)
	v_mfma_f32_32x32x16_bf16 v[96:111], v[244:247], v[164:167], v[96:111]
	ds_read_b128 v[252:255], v206 offset:10240
	s_waitcnt lgkmcnt(2)
	v_mfma_f32_32x32x16_bf16 v[96:111], v[190:193], v[160:163], v[96:111]
	ds_read_b128 v[236:239], v206 offset:12288
	s_waitcnt lgkmcnt(2)
	v_mfma_f32_32x32x16_bf16 v[96:111], v[194:197], v[156:159], v[96:111]
	ds_read_b128 v[240:243], v206 offset:14336
	s_waitcnt lgkmcnt(2)
	v_mfma_f32_32x32x16_bf16 v[96:111], v[252:255], v[152:155], v[96:111]
	ds_read_b128 v[244:247], v206 offset:1024
	s_waitcnt lgkmcnt(2)
	v_mfma_f32_32x32x16_bf16 v[96:111], v[236:239], v[148:151], v[96:111]
	ds_read_b128 v[190:193], v206 offset:3072
	s_waitcnt lgkmcnt(2)
	v_mfma_f32_32x32x16_bf16 v[96:111], v[240:243], v[144:147], v[96:111]
	ds_read_b128 v[194:197], v206 offset:5120
	s_waitcnt lgkmcnt(2)
	v_mfma_f32_32x32x16_bf16 v[112:127], v[244:247], v[172:175], v[16:31]
	ds_read_b128 v[252:255], v206 offset:7168
	s_waitcnt lgkmcnt(2)
	v_mfma_f32_32x32x16_bf16 v[112:127], v[190:193], v[168:171], v[112:127]
	ds_read_b128 v[236:239], v206 offset:9216
	s_waitcnt lgkmcnt(2)
	v_mfma_f32_32x32x16_bf16 v[112:127], v[194:197], v[164:167], v[112:127]
	ds_read_b128 v[240:243], v206 offset:11264
	s_waitcnt lgkmcnt(2)
	v_mfma_f32_32x32x16_bf16 v[112:127], v[252:255], v[160:163], v[112:127]
	ds_read_b128 v[244:247], v206 offset:13312
	s_waitcnt lgkmcnt(2)
	v_mfma_f32_32x32x16_bf16 v[112:127], v[236:239], v[156:159], v[112:127]
	ds_read_b128 v[190:193], v206 offset:15360
	s_waitcnt lgkmcnt(2)
	v_mfma_f32_32x32x16_bf16 v[112:127], v[240:243], v[152:155], v[112:127]
	s_waitcnt lgkmcnt(1)
	v_mfma_f32_32x32x16_bf16 v[112:127], v[244:247], v[148:151], v[112:127]
	s_waitcnt lgkmcnt(0)
	v_mfma_f32_32x32x16_bf16 v[112:127], v[190:193], v[144:147], v[112:127]
	ds_read_b128 v[236:239], v206 offset:16384
	ds_read_b128 v[240:243], v206 offset:18432
	ds_read_b128 v[244:247], v206 offset:20480
	v_exp_f32_e32 v96, v96
	v_exp_f32_e32 v97, v97
	v_exp_f32_e32 v98, v98
	v_exp_f32_e32 v99, v99
	v_exp_f32_e32 v100, v100
	v_exp_f32_e32 v101, v101
	v_exp_f32_e32 v102, v102
	v_exp_f32_e32 v103, v103
	v_exp_f32_e32 v104, v104
	v_exp_f32_e32 v105, v105
	v_exp_f32_e32 v106, v106
	v_exp_f32_e32 v107, v107
	v_exp_f32_e32 v108, v108
	v_exp_f32_e32 v109, v109
	v_exp_f32_e32 v110, v110
	v_exp_f32_e32 v111, v111
	v_exp_f32_e32 v112, v112
	v_exp_f32_e32 v113, v113
	v_exp_f32_e32 v114, v114
	v_exp_f32_e32 v115, v115
	v_exp_f32_e32 v116, v116
	v_exp_f32_e32 v117, v117
	v_exp_f32_e32 v118, v118
	v_exp_f32_e32 v119, v119
	v_exp_f32_e32 v120, v120
	v_exp_f32_e32 v121, v121
	v_exp_f32_e32 v122, v122
	v_exp_f32_e32 v123, v123
	v_exp_f32_e32 v124, v124
	v_exp_f32_e32 v125, v125
	v_exp_f32_e32 v126, v126
	v_exp_f32_e32 v127, v127
	s_cmp_lt_u32 s33, 4
	s_cbranch_scc1 .Lattn_lead_in
	s_setprio 1
	s_barrier
.Lattn_lead_in:
	s_movk_i32 s98, 63
.Lattn_loop:
	s_waitcnt lgkmcnt(2)
	v_mfma_f32_32x32x16_bf16 v[128:143], v[236:239], v[172:175], v[16:31]
	ds_read_b128 v[190:193], v206 offset:22528
	s_add_i32 m0, s74, 0
	v_cvt_pk_bf16_f32 v220, v96, v97
	v_cvt_pk_bf16_f32 v221, v98, v99
	v_cvt_pk_bf16_f32 v222, v100, v101
	global_load_lds_dwordx4 v180, s[72:73]
	s_waitcnt lgkmcnt(2)
	v_mfma_f32_32x32x16_bf16 v[128:143], v[240:243], v[168:171], v[128:143]
	ds_read_b128 v[194:197], v206 offset:24576
	s_add_i32 m0, s74, 8192
	v_cvt_pk_bf16_f32 v223, v102, v103
	v_add_f32_e32 v218, v96, v218
	v_add_f32_e32 v248, v97, v248
	global_load_lds_dwordx4 v198, s[72:73]
	s_add_u32 s72, s72, 0x90000
	s_addc_u32 s73, s73, 0
	s_waitcnt lgkmcnt(2)
	v_mfma_f32_32x32x16_bf16 v[128:143], v[244:247], v[164:167], v[128:143]
	ds_read_b128 v[252:255], v206 offset:26624
	v_add_f32_e32 v218, v98, v218
	v_add_f32_e32 v248, v99, v248
	v_add_f32_e32 v218, v100, v218
	s_waitcnt lgkmcnt(2)
	v_mfma_f32_32x32x16_bf16 v[128:143], v[190:193], v[160:163], v[128:143]
	ds_read_b128 v[236:239], v206 offset:28672
	v_add_f32_e32 v248, v101, v248
	v_add_f32_e32 v218, v102, v218
	v_add_f32_e32 v248, v103, v248
	s_waitcnt lgkmcnt(2)
	v_mfma_f32_32x32x16_bf16 v[128:143], v[194:197], v[156:159], v[128:143]
	ds_read_b128 v[240:243], v206 offset:30720
	v_cvt_pk_bf16_f32 v224, v104, v105
	v_cvt_pk_bf16_f32 v225, v106, v107
	v_cvt_pk_bf16_f32 v226, v108, v109
	s_waitcnt lgkmcnt(2)
	v_mfma_f32_32x32x16_bf16 v[128:143], v[252:255], v[152:155], v[128:143]
	ds_read_b128 v[244:247], v206 offset:17408
	v_cvt_pk_bf16_f32 v227, v110, v111
	v_add_f32_e32 v218, v104, v218
	v_add_f32_e32 v248, v105, v248
	s_waitcnt lgkmcnt(2)
	v_mfma_f32_32x32x16_bf16 v[128:143], v[236:239], v[148:151], v[128:143]
	ds_read_b128 v[190:193], v206 offset:19456
	v_add_f32_e32 v218, v106, v218
	v_add_f32_e32 v248, v107, v248
	v_add_f32_e32 v218, v108, v218
	s_waitcnt lgkmcnt(2)
	v_mfma_f32_32x32x16_bf16 v[128:143], v[240:243], v[144:147], v[128:143]
	ds_read_b128 v[194:197], v206 offset:21504
	v_add_f32_e32 v248, v109, v248
	v_add_f32_e32 v218, v110, v218
	v_add_f32_e32 v248, v111, v248
	s_waitcnt lgkmcnt(2)
	v_mfma_f32_32x32x16_bf16 v[0:15], v[244:247], v[172:175], v[16:31]
	ds_read_b128 v[252:255], v206 offset:23552
	v_cvt_pk_bf16_f32 v228, v112, v113
	v_cvt_pk_bf16_f32 v229, v114, v115
	v_cvt_pk_bf16_f32 v230, v116, v117
	s_waitcnt lgkmcnt(2)
	v_mfma_f32_32x32x16_bf16 v[0:15], v[190:193], v[168:171], v[0:15]
	ds_read_b128 v[236:239], v206 offset:25600
	v_cvt_pk_bf16_f32 v231, v118, v119
	v_add_f32_e32 v249, v112, v249
	v_add_f32_e32 v251, v113, v251
	s_waitcnt lgkmcnt(2)
	v_mfma_f32_32x32x16_bf16 v[0:15], v[194:197], v[164:167], v[0:15]
	ds_read_b128 v[240:243], v206 offset:27648
	v_add_f32_e32 v249, v114, v249
	v_add_f32_e32 v251, v115, v251
	v_add_f32_e32 v249, v116, v249
	s_waitcnt lgkmcnt(2)
	v_mfma_f32_32x32x16_bf16 v[0:15], v[252:255], v[160:163], v[0:15]
	ds_read_b128 v[244:247], v206 offset:29696
	v_add_f32_e32 v251, v117, v251
	v_add_f32_e32 v249, v118, v249
	v_add_f32_e32 v251, v119, v251
	s_waitcnt lgkmcnt(2)
	v_mfma_f32_32x32x16_bf16 v[0:15], v[236:239], v[156:159], v[0:15]
	ds_read_b128 v[190:193], v206 offset:31744
	v_cvt_pk_bf16_f32 v232, v120, v121
	v_cvt_pk_bf16_f32 v233, v122, v123
	v_cvt_pk_bf16_f32 v234, v124, v125
	s_waitcnt lgkmcnt(2)
	v_mfma_f32_32x32x16_bf16 v[0:15], v[240:243], v[152:155], v[0:15]
	ds_read_b64_tr_b16 v[194:195], v201 offset:0
	ds_read_b64_tr_b16 v[196:197], v201 offset:2048
	v_cvt_pk_bf16_f32 v235, v126, v127
	v_add_f32_e32 v249, v120, v249
	v_add_f32_e32 v251, v121, v251
	s_waitcnt lgkmcnt(3)
	v_mfma_f32_32x32x16_bf16 v[0:15], v[244:247], v[148:151], v[0:15]
	ds_read_b64_tr_b16 v[252:253], v201 offset:4096
	ds_read_b64_tr_b16 v[254:255], v201 offset:6144
	v_add_f32_e32 v249, v122, v249
	v_add_f32_e32 v251, v123, v251
	v_add_f32_e32 v249, v124, v249
	s_waitcnt lgkmcnt(4)
	v_mfma_f32_32x32x16_bf16 v[0:15], v[190:193], v[144:147], v[0:15]
	ds_read_b64_tr_b16 v[236:237], v201 offset:8192
	ds_read_b64_tr_b16 v[238:239], v201 offset:10240
	v_add_f32_e32 v251, v125, v251
	v_add_f32_e32 v249, v126, v249
	v_add_f32_e32 v251, v127, v251
	s_waitcnt vmcnt(6)
	s_barrier
	s_waitcnt lgkmcnt(4)
	v_mfma_f32_32x32x16_bf16 v[80:95], v[220:223], v[194:197], v[80:95]
	ds_read_b64_tr_b16 v[240:241], v201 offset:12288
	ds_read_b64_tr_b16 v[242:243], v201 offset:14336
	s_add_i32 m0, s68, 49152
	v_exp_f32_e32 v128, v128
	v_exp_f32_e32 v129, v129
	global_load_lds_dwordx4 v199, s[70:71]
	s_waitcnt lgkmcnt(4)
	v_mfma_f32_32x32x16_bf16 v[80:95], v[224:227], v[252:255], v[80:95]
	ds_read_b64_tr_b16 v[244:245], v201 offset:512
	ds_read_b64_tr_b16 v[246:247], v201 offset:2560
	s_add_i32 m0, s68, 57344
	v_exp_f32_e32 v130, v130
	v_exp_f32_e32 v131, v131
	global_load_lds_dwordx4 v219, s[70:71]
	s_add_u32 s70, s70, 0x90000
	s_addc_u32 s71, s71, 0
	s_waitcnt lgkmcnt(4)
	v_mfma_f32_32x32x16_bf16 v[80:95], v[228:231], v[236:239], v[80:95]
	ds_read_b64_tr_b16 v[190:191], v201 offset:4608
	ds_read_b64_tr_b16 v[192:193], v201 offset:6656
	v_exp_f32_e32 v132, v132
	v_exp_f32_e32 v133, v133
	s_waitcnt lgkmcnt(4)
	v_mfma_f32_32x32x16_bf16 v[80:95], v[232:235], v[240:243], v[80:95]
	ds_read_b64_tr_b16 v[194:195], v201 offset:8704
	ds_read_b64_tr_b16 v[196:197], v201 offset:10752
	v_exp_f32_e32 v134, v134
	v_exp_f32_e32 v135, v135
	s_waitcnt lgkmcnt(4)
	v_mfma_f32_32x32x16_bf16 v[64:79], v[220:223], v[244:247], v[64:79]
	ds_read_b64_tr_b16 v[252:253], v201 offset:12800
	ds_read_b64_tr_b16 v[254:255], v201 offset:14848
	v_exp_f32_e32 v136, v136
	v_exp_f32_e32 v137, v137
	s_waitcnt lgkmcnt(4)
	v_mfma_f32_32x32x16_bf16 v[64:79], v[224:227], v[190:193], v[64:79]
	ds_read_b64_tr_b16 v[236:237], v201 offset:1024
	ds_read_b64_tr_b16 v[238:239], v201 offset:3072
	v_exp_f32_e32 v138, v138
	v_exp_f32_e32 v139, v139
	s_waitcnt lgkmcnt(4)
	v_mfma_f32_32x32x16_bf16 v[64:79], v[228:231], v[194:197], v[64:79]
	ds_read_b64_tr_b16 v[240:241], v201 offset:5120
	ds_read_b64_tr_b16 v[242:243], v201 offset:7168
	v_exp_f32_e32 v140, v140
	v_exp_f32_e32 v141, v141
	s_waitcnt lgkmcnt(4)
	v_mfma_f32_32x32x16_bf16 v[64:79], v[232:235], v[252:255], v[64:79]
	ds_read_b64_tr_b16 v[244:245], v201 offset:9216
	ds_read_b64_tr_b16 v[246:247], v201 offset:11264
	v_exp_f32_e32 v142, v142
	v_exp_f32_e32 v143, v143
	s_waitcnt lgkmcnt(4)
	v_mfma_f32_32x32x16_bf16 v[48:63], v[220:223], v[236:239], v[48:63]
	ds_read_b64_tr_b16 v[236:237], v201 offset:13312
	ds_read_b64_tr_b16 v[238:239], v201 offset:15360
	ds_read_b64_tr_b16 v[190:191], v201 offset:5632
	ds_read_b64_tr_b16 v[192:193], v201 offset:7680
	v_exp_f32_e32 v0, v0
	v_exp_f32_e32 v1, v1
	s_waitcnt lgkmcnt(6)
	v_mfma_f32_32x32x16_bf16 v[48:63], v[224:227], v[240:243], v[48:63]
	ds_read_b64_tr_b16 v[240:241], v201 offset:1536
	ds_read_b64_tr_b16 v[242:243], v201 offset:3584
	ds_read_b64_tr_b16 v[194:195], v201 offset:9728
	ds_read_b64_tr_b16 v[196:197], v201 offset:11776
	v_exp_f32_e32 v2, v2
	v_exp_f32_e32 v3, v3
	s_waitcnt lgkmcnt(8)
	v_mfma_f32_32x32x16_bf16 v[48:63], v[228:231], v[244:247], v[48:63]
	ds_read_b64_tr_b16 v[252:253], v201 offset:13824
	ds_read_b64_tr_b16 v[254:255], v201 offset:15872
	v_exp_f32_e32 v4, v4
	v_exp_f32_e32 v5, v5
	s_waitcnt lgkmcnt(8)
	v_mfma_f32_32x32x16_bf16 v[48:63], v[232:235], v[236:239], v[48:63]
	v_exp_f32_e32 v6, v6
	v_exp_f32_e32 v7, v7
	s_waitcnt lgkmcnt(4)
	v_mfma_f32_32x32x16_bf16 v[32:47], v[220:223], v[240:243], v[32:47]
	v_exp_f32_e32 v8, v8
	v_exp_f32_e32 v9, v9
	s_waitcnt vmcnt(8) lgkmcnt(0)
	s_barrier
	ds_read_b128 v[236:239], v206 offset:32768
	ds_read_b128 v[240:243], v206 offset:34816
	ds_read_b128 v[244:247], v206 offset:36864
	v_mfma_f32_32x32x16_bf16 v[32:47], v[224:227], v[190:193], v[32:47]
	v_exp_f32_e32 v10, v10
	v_exp_f32_e32 v11, v11
	v_mfma_f32_32x32x16_bf16 v[32:47], v[228:231], v[194:197], v[32:47]
	v_exp_f32_e32 v12, v12
	v_exp_f32_e32 v13, v13
	v_mfma_f32_32x32x16_bf16 v[32:47], v[232:235], v[252:255], v[32:47]
	v_exp_f32_e32 v14, v14
	v_exp_f32_e32 v15, v15
	s_waitcnt lgkmcnt(2)
	v_mfma_f32_32x32x16_bf16 v[96:111], v[236:239], v[172:175], v[16:31]
	ds_read_b128 v[190:193], v206 offset:38912
	s_add_i32 m0, s74, 16384
	v_cvt_pk_bf16_f32 v220, v128, v129
	v_cvt_pk_bf16_f32 v221, v130, v131
	v_cvt_pk_bf16_f32 v222, v132, v133
	global_load_lds_dwordx4 v180, s[72:73]
	s_waitcnt lgkmcnt(2)
	v_mfma_f32_32x32x16_bf16 v[96:111], v[240:243], v[168:171], v[96:111]
	ds_read_b128 v[194:197], v206 offset:40960
	s_add_i32 m0, s74, 24576
	v_cvt_pk_bf16_f32 v223, v134, v135
	v_add_f32_e32 v218, v128, v218
	v_add_f32_e32 v248, v129, v248
	global_load_lds_dwordx4 v198, s[72:73]
	s_add_u32 s72, s72, 0x90000
	s_addc_u32 s73, s73, 0
	s_waitcnt lgkmcnt(2)
	v_mfma_f32_32x32x16_bf16 v[96:111], v[244:247], v[164:167], v[96:111]
	ds_read_b128 v[252:255], v206 offset:43008
	v_add_f32_e32 v218, v130, v218
	v_add_f32_e32 v248, v131, v248
	v_add_f32_e32 v218, v132, v218
	s_waitcnt lgkmcnt(2)
	v_mfma_f32_32x32x16_bf16 v[96:111], v[190:193], v[160:163], v[96:111]
	ds_read_b128 v[236:239], v206 offset:45056
	v_add_f32_e32 v248, v133, v248
	v_add_f32_e32 v218, v134, v218
	v_add_f32_e32 v248, v135, v248
	s_waitcnt lgkmcnt(2)
	v_mfma_f32_32x32x16_bf16 v[96:111], v[194:197], v[156:159], v[96:111]
	ds_read_b128 v[240:243], v206 offset:47104
	v_cvt_pk_bf16_f32 v224, v136, v137
	v_cvt_pk_bf16_f32 v225, v138, v139
	v_cvt_pk_bf16_f32 v226, v140, v141
	s_waitcnt lgkmcnt(2)
	v_mfma_f32_32x32x16_bf16 v[96:111], v[252:255], v[152:155], v[96:111]
	ds_read_b128 v[244:247], v206 offset:33792
	v_cvt_pk_bf16_f32 v227, v142, v143
	v_add_f32_e32 v218, v136, v218
	v_add_f32_e32 v248, v137, v248
	s_waitcnt lgkmcnt(2)
	v_mfma_f32_32x32x16_bf16 v[96:111], v[236:239], v[148:151], v[96:111]
	ds_read_b128 v[190:193], v206 offset:35840
	v_add_f32_e32 v218, v138, v218
	v_add_f32_e32 v248, v139, v248
	v_add_f32_e32 v218, v140, v218
	s_waitcnt lgkmcnt(2)
	v_mfma_f32_32x32x16_bf16 v[96:111], v[240:243], v[144:147], v[96:111]
	ds_read_b128 v[194:197], v206 offset:37888
	v_add_f32_e32 v248, v141, v248
	v_add_f32_e32 v218, v142, v218
	v_add_f32_e32 v248, v143, v248
	s_waitcnt lgkmcnt(2)
	v_mfma_f32_32x32x16_bf16 v[112:127], v[244:247], v[172:175], v[16:31]
	ds_read_b128 v[252:255], v206 offset:39936
	v_cvt_pk_bf16_f32 v228, v0, v1
	v_cvt_pk_bf16_f32 v229, v2, v3
	v_cvt_pk_bf16_f32 v230, v4, v5
	s_waitcnt lgkmcnt(2)
	v_mfma_f32_32x32x16_bf16 v[112:127], v[190:193], v[168:171], v[112:127]
	ds_read_b128 v[236:239], v206 offset:41984
	v_cvt_pk_bf16_f32 v231, v6, v7
	v_add_f32_e32 v249, v0, v249
	v_add_f32_e32 v251, v1, v251
	s_waitcnt lgkmcnt(2)
	v_mfma_f32_32x32x16_bf16 v[112:127], v[194:197], v[164:167], v[112:127]
	ds_read_b128 v[240:243], v206 offset:44032
	v_add_f32_e32 v249, v2, v249
	v_add_f32_e32 v251, v3, v251
	v_add_f32_e32 v249, v4, v249
	s_waitcnt lgkmcnt(2)
	v_mfma_f32_32x32x16_bf16 v[112:127], v[252:255], v[160:163], v[112:127]
	ds_read_b128 v[244:247], v206 offset:46080
	v_add_f32_e32 v251, v5, v251
	v_add_f32_e32 v249, v6, v249
	v_add_f32_e32 v251, v7, v251
	s_waitcnt lgkmcnt(2)
	v_mfma_f32_32x32x16_bf16 v[112:127], v[236:239], v[156:159], v[112:127]
	ds_read_b128 v[190:193], v206 offset:48128
	v_cvt_pk_bf16_f32 v232, v8, v9
	v_cvt_pk_bf16_f32 v233, v10, v11
	v_cvt_pk_bf16_f32 v234, v12, v13
	s_waitcnt lgkmcnt(2)
	v_mfma_f32_32x32x16_bf16 v[112:127], v[240:243], v[152:155], v[112:127]
	ds_read_b64_tr_b16 v[194:195], v201 offset:16384
	ds_read_b64_tr_b16 v[196:197], v201 offset:18432
	v_cvt_pk_bf16_f32 v235, v14, v15
	v_add_f32_e32 v249, v8, v249
	v_add_f32_e32 v251, v9, v251
	s_waitcnt lgkmcnt(3)
	v_mfma_f32_32x32x16_bf16 v[112:127], v[244:247], v[148:151], v[112:127]
	ds_read_b64_tr_b16 v[252:253], v201 offset:20480
	ds_read_b64_tr_b16 v[254:255], v201 offset:22528
	v_add_f32_e32 v249, v10, v249
	v_add_f32_e32 v251, v11, v251
	v_add_f32_e32 v249, v12, v249
	s_waitcnt lgkmcnt(4)
	v_mfma_f32_32x32x16_bf16 v[112:127], v[190:193], v[144:147], v[112:127]
	ds_read_b64_tr_b16 v[236:237], v201 offset:24576
	ds_read_b64_tr_b16 v[238:239], v201 offset:26624
	v_add_f32_e32 v251, v13, v251
	v_add_f32_e32 v249, v14, v249
	v_add_f32_e32 v251, v15, v251
	s_waitcnt vmcnt(6)
	s_barrier
	s_waitcnt lgkmcnt(4)
	v_mfma_f32_32x32x16_bf16 v[80:95], v[220:223], v[194:197], v[80:95]
	ds_read_b64_tr_b16 v[240:241], v201 offset:28672
	ds_read_b64_tr_b16 v[242:243], v201 offset:30720
	s_add_i32 m0, s68, 0
	v_exp_f32_e32 v96, v96
	v_exp_f32_e32 v97, v97
	global_load_lds_dwordx4 v199, s[70:71]
	s_waitcnt lgkmcnt(4)
	v_mfma_f32_32x32x16_bf16 v[80:95], v[224:227], v[252:255], v[80:95]
	ds_read_b64_tr_b16 v[244:245], v201 offset:16896
	ds_read_b64_tr_b16 v[246:247], v201 offset:18944
	s_add_i32 m0, s68, 8192
	v_exp_f32_e32 v98, v98
	v_exp_f32_e32 v99, v99
	global_load_lds_dwordx4 v219, s[70:71]
	s_add_u32 s70, s70, 0x90000
	s_addc_u32 s71, s71, 0
	s_waitcnt lgkmcnt(4)
	v_mfma_f32_32x32x16_bf16 v[80:95], v[228:231], v[236:239], v[80:95]
	ds_read_b64_tr_b16 v[190:191], v201 offset:20992
	ds_read_b64_tr_b16 v[192:193], v201 offset:23040
	v_exp_f32_e32 v100, v100
	v_exp_f32_e32 v101, v101
	s_waitcnt lgkmcnt(4)
	v_mfma_f32_32x32x16_bf16 v[80:95], v[232:235], v[240:243], v[80:95]
	ds_read_b64_tr_b16 v[194:195], v201 offset:25088
	ds_read_b64_tr_b16 v[196:197], v201 offset:27136
	v_exp_f32_e32 v102, v102
	v_exp_f32_e32 v103, v103
	s_waitcnt lgkmcnt(4)
	v_mfma_f32_32x32x16_bf16 v[64:79], v[220:223], v[244:247], v[64:79]
	ds_read_b64_tr_b16 v[252:253], v201 offset:29184
	ds_read_b64_tr_b16 v[254:255], v201 offset:31232
	v_exp_f32_e32 v104, v104
	v_exp_f32_e32 v105, v105
	s_waitcnt lgkmcnt(4)
	v_mfma_f32_32x32x16_bf16 v[64:79], v[224:227], v[190:193], v[64:79]
	ds_read_b64_tr_b16 v[236:237], v201 offset:17408
	ds_read_b64_tr_b16 v[238:239], v201 offset:19456
	v_exp_f32_e32 v106, v106
	v_exp_f32_e32 v107, v107
	s_waitcnt lgkmcnt(4)
	v_mfma_f32_32x32x16_bf16 v[64:79], v[228:231], v[194:197], v[64:79]
	ds_read_b64_tr_b16 v[240:241], v201 offset:21504
	ds_read_b64_tr_b16 v[242:243], v201 offset:23552
	v_exp_f32_e32 v108, v108
	v_exp_f32_e32 v109, v109
	s_waitcnt lgkmcnt(4)
	v_mfma_f32_32x32x16_bf16 v[64:79], v[232:235], v[252:255], v[64:79]
	ds_read_b64_tr_b16 v[244:245], v201 offset:25600
	ds_read_b64_tr_b16 v[246:247], v201 offset:27648
	v_exp_f32_e32 v110, v110
	v_exp_f32_e32 v111, v111
	s_waitcnt lgkmcnt(4)
	v_mfma_f32_32x32x16_bf16 v[48:63], v[220:223], v[236:239], v[48:63]
	ds_read_b64_tr_b16 v[236:237], v201 offset:29696
	ds_read_b64_tr_b16 v[238:239], v201 offset:31744
	ds_read_b64_tr_b16 v[190:191], v201 offset:22016
	ds_read_b64_tr_b16 v[192:193], v201 offset:24064
	v_exp_f32_e32 v112, v112
	v_exp_f32_e32 v113, v113
	s_waitcnt lgkmcnt(6)
	v_mfma_f32_32x32x16_bf16 v[48:63], v[224:227], v[240:243], v[48:63]
	ds_read_b64_tr_b16 v[240:241], v201 offset:17920
	ds_read_b64_tr_b16 v[242:243], v201 offset:19968
	ds_read_b64_tr_b16 v[194:195], v201 offset:26112
	ds_read_b64_tr_b16 v[196:197], v201 offset:28160
	v_exp_f32_e32 v114, v114
	v_exp_f32_e32 v115, v115
	s_waitcnt lgkmcnt(8)
	v_mfma_f32_32x32x16_bf16 v[48:63], v[228:231], v[244:247], v[48:63]
	ds_read_b64_tr_b16 v[252:253], v201 offset:30208
	ds_read_b64_tr_b16 v[254:255], v201 offset:32256
	v_exp_f32_e32 v116, v116
	v_exp_f32_e32 v117, v117
	s_waitcnt lgkmcnt(8)
	v_mfma_f32_32x32x16_bf16 v[48:63], v[232:235], v[236:239], v[48:63]
	v_exp_f32_e32 v118, v118
	v_exp_f32_e32 v119, v119
	s_waitcnt lgkmcnt(4)
	v_mfma_f32_32x32x16_bf16 v[32:47], v[220:223], v[240:243], v[32:47]
	v_exp_f32_e32 v120, v120
	v_exp_f32_e32 v121, v121
	s_waitcnt vmcnt(8) lgkmcnt(0)
	s_barrier
	ds_read_b128 v[236:239], v206 offset:49152
	ds_read_b128 v[240:243], v206 offset:51200
	ds_read_b128 v[244:247], v206 offset:53248
	v_mfma_f32_32x32x16_bf16 v[32:47], v[224:227], v[190:193], v[32:47]
	v_exp_f32_e32 v122, v122
	v_exp_f32_e32 v123, v123
	v_mfma_f32_32x32x16_bf16 v[32:47], v[228:231], v[194:197], v[32:47]
	v_exp_f32_e32 v124, v124
	v_exp_f32_e32 v125, v125
	v_mfma_f32_32x32x16_bf16 v[32:47], v[232:235], v[252:255], v[32:47]
	v_exp_f32_e32 v126, v126
	v_exp_f32_e32 v127, v127
	s_waitcnt lgkmcnt(2)
	v_mfma_f32_32x32x16_bf16 v[128:143], v[236:239], v[172:175], v[16:31]
	ds_read_b128 v[190:193], v206 offset:55296
	s_add_i32 m0, s74, 32768
	v_cvt_pk_bf16_f32 v220, v96, v97
	v_cvt_pk_bf16_f32 v221, v98, v99
	v_cvt_pk_bf16_f32 v222, v100, v101
	global_load_lds_dwordx4 v180, s[72:73]
	s_waitcnt lgkmcnt(2)
	v_mfma_f32_32x32x16_bf16 v[128:143], v[240:243], v[168:171], v[128:143]
	ds_read_b128 v[194:197], v206 offset:57344
	s_add_i32 m0, s74, 40960
	v_cvt_pk_bf16_f32 v223, v102, v103
	v_add_f32_e32 v218, v96, v218
	v_add_f32_e32 v248, v97, v248
	global_load_lds_dwordx4 v198, s[72:73]
	s_add_u32 s72, s72, 0x90000
	s_addc_u32 s73, s73, 0
	s_waitcnt lgkmcnt(2)
	v_mfma_f32_32x32x16_bf16 v[128:143], v[244:247], v[164:167], v[128:143]
	ds_read_b128 v[252:255], v206 offset:59392
	v_add_f32_e32 v218, v98, v218
	v_add_f32_e32 v248, v99, v248
	v_add_f32_e32 v218, v100, v218
	s_waitcnt lgkmcnt(2)
	v_mfma_f32_32x32x16_bf16 v[128:143], v[190:193], v[160:163], v[128:143]
	ds_read_b128 v[236:239], v206 offset:61440
	v_add_f32_e32 v248, v101, v248
	v_add_f32_e32 v218, v102, v218
	v_add_f32_e32 v248, v103, v248
	s_waitcnt lgkmcnt(2)
	v_mfma_f32_32x32x16_bf16 v[128:143], v[194:197], v[156:159], v[128:143]
	ds_read_b128 v[240:243], v206 offset:63488
	v_cvt_pk_bf16_f32 v224, v104, v105
	v_cvt_pk_bf16_f32 v225, v106, v107
	v_cvt_pk_bf16_f32 v226, v108, v109
	s_waitcnt lgkmcnt(2)
	v_mfma_f32_32x32x16_bf16 v[128:143], v[252:255], v[152:155], v[128:143]
	ds_read_b128 v[244:247], v206 offset:50176
	v_cvt_pk_bf16_f32 v227, v110, v111
	v_add_f32_e32 v218, v104, v218
	v_add_f32_e32 v248, v105, v248
	s_waitcnt lgkmcnt(2)
	v_mfma_f32_32x32x16_bf16 v[128:143], v[236:239], v[148:151], v[128:143]
	ds_read_b128 v[190:193], v206 offset:52224
	v_add_f32_e32 v218, v106, v218
	v_add_f32_e32 v248, v107, v248
	v_add_f32_e32 v218, v108, v218
	s_waitcnt lgkmcnt(2)
	v_mfma_f32_32x32x16_bf16 v[128:143], v[240:243], v[144:147], v[128:143]
	ds_read_b128 v[194:197], v206 offset:54272
	v_add_f32_e32 v248, v109, v248
	v_add_f32_e32 v218, v110, v218
	v_add_f32_e32 v248, v111, v248
	s_waitcnt lgkmcnt(2)
	v_mfma_f32_32x32x16_bf16 v[0:15], v[244:247], v[172:175], v[16:31]
	ds_read_b128 v[252:255], v206 offset:56320
	v_cvt_pk_bf16_f32 v228, v112, v113
	v_cvt_pk_bf16_f32 v229, v114, v115
	v_cvt_pk_bf16_f32 v230, v116, v117
	s_waitcnt lgkmcnt(2)
	v_mfma_f32_32x32x16_bf16 v[0:15], v[190:193], v[168:171], v[0:15]
	ds_read_b128 v[236:239], v206 offset:58368
	v_cvt_pk_bf16_f32 v231, v118, v119
	v_add_f32_e32 v249, v112, v249
	v_add_f32_e32 v251, v113, v251
	s_waitcnt lgkmcnt(2)
	v_mfma_f32_32x32x16_bf16 v[0:15], v[194:197], v[164:167], v[0:15]
	ds_read_b128 v[240:243], v206 offset:60416
	v_add_f32_e32 v249, v114, v249
	v_add_f32_e32 v251, v115, v251
	v_add_f32_e32 v249, v116, v249
	s_waitcnt lgkmcnt(2)
	v_mfma_f32_32x32x16_bf16 v[0:15], v[252:255], v[160:163], v[0:15]
	ds_read_b128 v[244:247], v206 offset:62464
	v_add_f32_e32 v251, v117, v251
	v_add_f32_e32 v249, v118, v249
	v_add_f32_e32 v251, v119, v251
	s_waitcnt lgkmcnt(2)
	v_mfma_f32_32x32x16_bf16 v[0:15], v[236:239], v[156:159], v[0:15]
	ds_read_b128 v[190:193], v206 offset:64512
	v_cvt_pk_bf16_f32 v232, v120, v121
	v_cvt_pk_bf16_f32 v233, v122, v123
	v_cvt_pk_bf16_f32 v234, v124, v125
	s_waitcnt lgkmcnt(2)
	v_mfma_f32_32x32x16_bf16 v[0:15], v[240:243], v[152:155], v[0:15]
	ds_read_b64_tr_b16 v[194:195], v201 offset:32768
	ds_read_b64_tr_b16 v[196:197], v201 offset:34816
	v_cvt_pk_bf16_f32 v235, v126, v127
	v_add_f32_e32 v249, v120, v249
	v_add_f32_e32 v251, v121, v251
	s_waitcnt lgkmcnt(3)
	v_mfma_f32_32x32x16_bf16 v[0:15], v[244:247], v[148:151], v[0:15]
	ds_read_b64_tr_b16 v[252:253], v201 offset:36864
	ds_read_b64_tr_b16 v[254:255], v201 offset:38912
	v_add_f32_e32 v249, v122, v249
	v_add_f32_e32 v251, v123, v251
	v_add_f32_e32 v249, v124, v249
	s_waitcnt lgkmcnt(4)
	v_mfma_f32_32x32x16_bf16 v[0:15], v[190:193], v[144:147], v[0:15]
	ds_read_b64_tr_b16 v[236:237], v201 offset:40960
	ds_read_b64_tr_b16 v[238:239], v201 offset:43008
	v_add_f32_e32 v251, v125, v251
	v_add_f32_e32 v249, v126, v249
	v_add_f32_e32 v251, v127, v251
	s_waitcnt vmcnt(6)
	s_barrier
	s_waitcnt lgkmcnt(4)
	v_mfma_f32_32x32x16_bf16 v[80:95], v[220:223], v[194:197], v[80:95]
	ds_read_b64_tr_b16 v[240:241], v201 offset:45056
	ds_read_b64_tr_b16 v[242:243], v201 offset:47104
	s_add_i32 m0, s68, 16384
	v_exp_f32_e32 v128, v128
	v_exp_f32_e32 v129, v129
	global_load_lds_dwordx4 v199, s[70:71]
	s_waitcnt lgkmcnt(4)
	v_mfma_f32_32x32x16_bf16 v[80:95], v[224:227], v[252:255], v[80:95]
	ds_read_b64_tr_b16 v[244:245], v201 offset:33280
	ds_read_b64_tr_b16 v[246:247], v201 offset:35328
	s_add_i32 m0, s68, 24576
	v_exp_f32_e32 v130, v130
	v_exp_f32_e32 v131, v131
	global_load_lds_dwordx4 v219, s[70:71]
	s_add_u32 s70, s70, 0x90000
	s_addc_u32 s71, s71, 0
	s_waitcnt lgkmcnt(4)
	v_mfma_f32_32x32x16_bf16 v[80:95], v[228:231], v[236:239], v[80:95]
	ds_read_b64_tr_b16 v[190:191], v201 offset:37376
	ds_read_b64_tr_b16 v[192:193], v201 offset:39424
	v_exp_f32_e32 v132, v132
	v_exp_f32_e32 v133, v133
	s_waitcnt lgkmcnt(4)
	v_mfma_f32_32x32x16_bf16 v[80:95], v[232:235], v[240:243], v[80:95]
	ds_read_b64_tr_b16 v[194:195], v201 offset:41472
	ds_read_b64_tr_b16 v[196:197], v201 offset:43520
	v_exp_f32_e32 v134, v134
	v_exp_f32_e32 v135, v135
	s_waitcnt lgkmcnt(4)
	v_mfma_f32_32x32x16_bf16 v[64:79], v[220:223], v[244:247], v[64:79]
	ds_read_b64_tr_b16 v[252:253], v201 offset:45568
	ds_read_b64_tr_b16 v[254:255], v201 offset:47616
	v_exp_f32_e32 v136, v136
	v_exp_f32_e32 v137, v137
	s_waitcnt lgkmcnt(4)
	v_mfma_f32_32x32x16_bf16 v[64:79], v[224:227], v[190:193], v[64:79]
	ds_read_b64_tr_b16 v[236:237], v201 offset:33792
	ds_read_b64_tr_b16 v[238:239], v201 offset:35840
	v_exp_f32_e32 v138, v138
	v_exp_f32_e32 v139, v139
	s_waitcnt lgkmcnt(4)
	v_mfma_f32_32x32x16_bf16 v[64:79], v[228:231], v[194:197], v[64:79]
	ds_read_b64_tr_b16 v[240:241], v201 offset:37888
	ds_read_b64_tr_b16 v[242:243], v201 offset:39936
	v_exp_f32_e32 v140, v140
	v_exp_f32_e32 v141, v141
	s_waitcnt lgkmcnt(4)
	v_mfma_f32_32x32x16_bf16 v[64:79], v[232:235], v[252:255], v[64:79]
	ds_read_b64_tr_b16 v[244:245], v201 offset:41984
	ds_read_b64_tr_b16 v[246:247], v201 offset:44032
	v_exp_f32_e32 v142, v142
	v_exp_f32_e32 v143, v143
	s_waitcnt lgkmcnt(4)
	v_mfma_f32_32x32x16_bf16 v[48:63], v[220:223], v[236:239], v[48:63]
	ds_read_b64_tr_b16 v[236:237], v201 offset:46080
	ds_read_b64_tr_b16 v[238:239], v201 offset:48128
	ds_read_b64_tr_b16 v[190:191], v201 offset:38400
	ds_read_b64_tr_b16 v[192:193], v201 offset:40448
	v_exp_f32_e32 v0, v0
	v_exp_f32_e32 v1, v1
	s_waitcnt lgkmcnt(6)
	v_mfma_f32_32x32x16_bf16 v[48:63], v[224:227], v[240:243], v[48:63]
	ds_read_b64_tr_b16 v[240:241], v201 offset:34304
	ds_read_b64_tr_b16 v[242:243], v201 offset:36352
	ds_read_b64_tr_b16 v[194:195], v201 offset:42496
	ds_read_b64_tr_b16 v[196:197], v201 offset:44544
	v_exp_f32_e32 v2, v2
	v_exp_f32_e32 v3, v3
	s_waitcnt lgkmcnt(8)
	v_mfma_f32_32x32x16_bf16 v[48:63], v[228:231], v[244:247], v[48:63]
	ds_read_b64_tr_b16 v[252:253], v201 offset:46592
	ds_read_b64_tr_b16 v[254:255], v201 offset:48640
	v_exp_f32_e32 v4, v4
	v_exp_f32_e32 v5, v5
	s_waitcnt lgkmcnt(8)
	v_mfma_f32_32x32x16_bf16 v[48:63], v[232:235], v[236:239], v[48:63]
	v_exp_f32_e32 v6, v6
	v_exp_f32_e32 v7, v7
	s_waitcnt lgkmcnt(4)
	v_mfma_f32_32x32x16_bf16 v[32:47], v[220:223], v[240:243], v[32:47]
	v_exp_f32_e32 v8, v8
	v_exp_f32_e32 v9, v9
	s_waitcnt vmcnt(8) lgkmcnt(0)
	s_barrier
	ds_read_b128 v[236:239], v206 offset:0
	ds_read_b128 v[240:243], v206 offset:2048
	ds_read_b128 v[244:247], v206 offset:4096
	v_mfma_f32_32x32x16_bf16 v[32:47], v[224:227], v[190:193], v[32:47]
	v_exp_f32_e32 v10, v10
	v_exp_f32_e32 v11, v11
	v_mfma_f32_32x32x16_bf16 v[32:47], v[228:231], v[194:197], v[32:47]
	v_exp_f32_e32 v12, v12
	v_exp_f32_e32 v13, v13
	v_mfma_f32_32x32x16_bf16 v[32:47], v[232:235], v[252:255], v[32:47]
	v_exp_f32_e32 v14, v14
	v_exp_f32_e32 v15, v15
	s_waitcnt lgkmcnt(2)
	v_mfma_f32_32x32x16_bf16 v[96:111], v[236:239], v[172:175], v[16:31]
	ds_read_b128 v[190:193], v206 offset:6144
	s_add_i32 m0, s74, 49152
	v_cvt_pk_bf16_f32 v220, v128, v129
	v_cvt_pk_bf16_f32 v221, v130, v131
	v_cvt_pk_bf16_f32 v222, v132, v133
	global_load_lds_dwordx4 v180, s[72:73]
	s_waitcnt lgkmcnt(2)
	v_mfma_f32_32x32x16_bf16 v[96:111], v[240:243], v[168:171], v[96:111]
	ds_read_b128 v[194:197], v206 offset:8192
	s_add_i32 m0, s74, 57344
	v_cvt_pk_bf16_f32 v223, v134, v135
	v_add_f32_e32 v218, v128, v218
	v_add_f32_e32 v248, v129, v248
	global_load_lds_dwordx4 v198, s[72:73]
	s_add_u32 s72, s72, 0x90000
	s_addc_u32 s73, s73, 0
	s_waitcnt lgkmcnt(2)
	v_mfma_f32_32x32x16_bf16 v[96:111], v[244:247], v[164:167], v[96:111]
	ds_read_b128 v[252:255], v206 offset:10240
	v_add_f32_e32 v218, v130, v218
	v_add_f32_e32 v248, v131, v248
	v_add_f32_e32 v218, v132, v218
	s_waitcnt lgkmcnt(2)
	v_mfma_f32_32x32x16_bf16 v[96:111], v[190:193], v[160:163], v[96:111]
	ds_read_b128 v[236:239], v206 offset:12288
	v_add_f32_e32 v248, v133, v248
	v_add_f32_e32 v218, v134, v218
	v_add_f32_e32 v248, v135, v248
	s_waitcnt lgkmcnt(2)
	v_mfma_f32_32x32x16_bf16 v[96:111], v[194:197], v[156:159], v[96:111]
	ds_read_b128 v[240:243], v206 offset:14336
	v_cvt_pk_bf16_f32 v224, v136, v137
	v_cvt_pk_bf16_f32 v225, v138, v139
	v_cvt_pk_bf16_f32 v226, v140, v141
	s_waitcnt lgkmcnt(2)
	v_mfma_f32_32x32x16_bf16 v[96:111], v[252:255], v[152:155], v[96:111]
	ds_read_b128 v[244:247], v206 offset:1024
	v_cvt_pk_bf16_f32 v227, v142, v143
	v_add_f32_e32 v218, v136, v218
	v_add_f32_e32 v248, v137, v248
	s_waitcnt lgkmcnt(2)
	v_mfma_f32_32x32x16_bf16 v[96:111], v[236:239], v[148:151], v[96:111]
	ds_read_b128 v[190:193], v206 offset:3072
	v_add_f32_e32 v218, v138, v218
	v_add_f32_e32 v248, v139, v248
	v_add_f32_e32 v218, v140, v218
	s_waitcnt lgkmcnt(2)
	v_mfma_f32_32x32x16_bf16 v[96:111], v[240:243], v[144:147], v[96:111]
	ds_read_b128 v[194:197], v206 offset:5120
	v_add_f32_e32 v248, v141, v248
	v_add_f32_e32 v218, v142, v218
	v_add_f32_e32 v248, v143, v248
	s_waitcnt lgkmcnt(2)
	v_mfma_f32_32x32x16_bf16 v[112:127], v[244:247], v[172:175], v[16:31]
	ds_read_b128 v[252:255], v206 offset:7168
	v_cvt_pk_bf16_f32 v228, v0, v1
	v_cvt_pk_bf16_f32 v229, v2, v3
	v_cvt_pk_bf16_f32 v230, v4, v5
	s_waitcnt lgkmcnt(2)
	v_mfma_f32_32x32x16_bf16 v[112:127], v[190:193], v[168:171], v[112:127]
	ds_read_b128 v[236:239], v206 offset:9216
	v_cvt_pk_bf16_f32 v231, v6, v7
	v_add_f32_e32 v249, v0, v249
	v_add_f32_e32 v251, v1, v251
	s_waitcnt lgkmcnt(2)
	v_mfma_f32_32x32x16_bf16 v[112:127], v[194:197], v[164:167], v[112:127]
	ds_read_b128 v[240:243], v206 offset:11264
	v_add_f32_e32 v249, v2, v249
	v_add_f32_e32 v251, v3, v251
	v_add_f32_e32 v249, v4, v249
	s_waitcnt lgkmcnt(2)
	v_mfma_f32_32x32x16_bf16 v[112:127], v[252:255], v[160:163], v[112:127]
	ds_read_b128 v[244:247], v206 offset:13312
	v_add_f32_e32 v251, v5, v251
	v_add_f32_e32 v249, v6, v249
	v_add_f32_e32 v251, v7, v251
	s_waitcnt lgkmcnt(2)
	v_mfma_f32_32x32x16_bf16 v[112:127], v[236:239], v[156:159], v[112:127]
	ds_read_b128 v[190:193], v206 offset:15360
	v_cvt_pk_bf16_f32 v232, v8, v9
	v_cvt_pk_bf16_f32 v233, v10, v11
	v_cvt_pk_bf16_f32 v234, v12, v13
	s_waitcnt lgkmcnt(2)
	v_mfma_f32_32x32x16_bf16 v[112:127], v[240:243], v[152:155], v[112:127]
	ds_read_b64_tr_b16 v[194:195], v201 offset:49152
	ds_read_b64_tr_b16 v[196:197], v201 offset:51200
	v_cvt_pk_bf16_f32 v235, v14, v15
	v_add_f32_e32 v249, v8, v249
	v_add_f32_e32 v251, v9, v251
	s_waitcnt lgkmcnt(3)
	v_mfma_f32_32x32x16_bf16 v[112:127], v[244:247], v[148:151], v[112:127]
	ds_read_b64_tr_b16 v[252:253], v201 offset:53248
	ds_read_b64_tr_b16 v[254:255], v201 offset:55296
	v_add_f32_e32 v249, v10, v249
	v_add_f32_e32 v251, v11, v251
	v_add_f32_e32 v249, v12, v249
	s_waitcnt lgkmcnt(4)
	v_mfma_f32_32x32x16_bf16 v[112:127], v[190:193], v[144:147], v[112:127]
	ds_read_b64_tr_b16 v[236:237], v201 offset:57344
	ds_read_b64_tr_b16 v[238:239], v201 offset:59392
	v_add_f32_e32 v251, v13, v251
	v_add_f32_e32 v249, v14, v249
	v_add_f32_e32 v251, v15, v251
	s_waitcnt vmcnt(6)
	s_barrier
	s_waitcnt lgkmcnt(4)
	v_mfma_f32_32x32x16_bf16 v[80:95], v[220:223], v[194:197], v[80:95]
	ds_read_b64_tr_b16 v[240:241], v201 offset:61440
	ds_read_b64_tr_b16 v[242:243], v201 offset:63488
	s_add_i32 m0, s68, 32768
	v_exp_f32_e32 v96, v96
	v_exp_f32_e32 v97, v97
	global_load_lds_dwordx4 v199, s[70:71]
	s_waitcnt lgkmcnt(4)
	v_mfma_f32_32x32x16_bf16 v[80:95], v[224:227], v[252:255], v[80:95]
	ds_read_b64_tr_b16 v[244:245], v201 offset:49664
	ds_read_b64_tr_b16 v[246:247], v201 offset:51712
	s_add_i32 m0, s68, 40960
	v_exp_f32_e32 v98, v98
	v_exp_f32_e32 v99, v99
	global_load_lds_dwordx4 v219, s[70:71]
	s_add_u32 s70, s70, 0x90000
	s_addc_u32 s71, s71, 0
	s_waitcnt lgkmcnt(4)
	v_mfma_f32_32x32x16_bf16 v[80:95], v[228:231], v[236:239], v[80:95]
	ds_read_b64_tr_b16 v[190:191], v201 offset:53760
	ds_read_b64_tr_b16 v[192:193], v201 offset:55808
	v_exp_f32_e32 v100, v100
	v_exp_f32_e32 v101, v101
	s_waitcnt lgkmcnt(4)
	v_mfma_f32_32x32x16_bf16 v[80:95], v[232:235], v[240:243], v[80:95]
	ds_read_b64_tr_b16 v[194:195], v201 offset:57856
	ds_read_b64_tr_b16 v[196:197], v201 offset:59904
	v_exp_f32_e32 v102, v102
	v_exp_f32_e32 v103, v103
	s_waitcnt lgkmcnt(4)
	v_mfma_f32_32x32x16_bf16 v[64:79], v[220:223], v[244:247], v[64:79]
	ds_read_b64_tr_b16 v[252:253], v201 offset:61952
	ds_read_b64_tr_b16 v[254:255], v201 offset:64000
	v_exp_f32_e32 v104, v104
	v_exp_f32_e32 v105, v105
	s_waitcnt lgkmcnt(4)
	v_mfma_f32_32x32x16_bf16 v[64:79], v[224:227], v[190:193], v[64:79]
	ds_read_b64_tr_b16 v[236:237], v201 offset:50176
	ds_read_b64_tr_b16 v[238:239], v201 offset:52224
	v_exp_f32_e32 v106, v106
	v_exp_f32_e32 v107, v107
	s_waitcnt lgkmcnt(4)
	v_mfma_f32_32x32x16_bf16 v[64:79], v[228:231], v[194:197], v[64:79]
	ds_read_b64_tr_b16 v[240:241], v201 offset:54272
	ds_read_b64_tr_b16 v[242:243], v201 offset:56320
	v_exp_f32_e32 v108, v108
	v_exp_f32_e32 v109, v109
	s_waitcnt lgkmcnt(4)
	v_mfma_f32_32x32x16_bf16 v[64:79], v[232:235], v[252:255], v[64:79]
	ds_read_b64_tr_b16 v[244:245], v201 offset:58368
	ds_read_b64_tr_b16 v[246:247], v201 offset:60416
	v_exp_f32_e32 v110, v110
	v_exp_f32_e32 v111, v111
	s_waitcnt lgkmcnt(4)
	v_mfma_f32_32x32x16_bf16 v[48:63], v[220:223], v[236:239], v[48:63]
	ds_read_b64_tr_b16 v[236:237], v201 offset:62464
	ds_read_b64_tr_b16 v[238:239], v201 offset:64512
	ds_read_b64_tr_b16 v[190:191], v201 offset:54784
	ds_read_b64_tr_b16 v[192:193], v201 offset:56832
	v_exp_f32_e32 v112, v112
	v_exp_f32_e32 v113, v113
	s_waitcnt lgkmcnt(6)
	v_mfma_f32_32x32x16_bf16 v[48:63], v[224:227], v[240:243], v[48:63]
	ds_read_b64_tr_b16 v[240:241], v201 offset:50688
	ds_read_b64_tr_b16 v[242:243], v201 offset:52736
	ds_read_b64_tr_b16 v[194:195], v201 offset:58880
	ds_read_b64_tr_b16 v[196:197], v201 offset:60928
	v_exp_f32_e32 v114, v114
	v_exp_f32_e32 v115, v115
	s_waitcnt lgkmcnt(8)
	v_mfma_f32_32x32x16_bf16 v[48:63], v[228:231], v[244:247], v[48:63]
	ds_read_b64_tr_b16 v[252:253], v201 offset:62976
	ds_read_b64_tr_b16 v[254:255], v201 offset:65024
	v_exp_f32_e32 v116, v116
	v_exp_f32_e32 v117, v117
	s_waitcnt lgkmcnt(8)
	v_mfma_f32_32x32x16_bf16 v[48:63], v[232:235], v[236:239], v[48:63]
	v_exp_f32_e32 v118, v118
	v_exp_f32_e32 v119, v119
	s_waitcnt lgkmcnt(4)
	v_mfma_f32_32x32x16_bf16 v[32:47], v[220:223], v[240:243], v[32:47]
	v_exp_f32_e32 v120, v120
	v_exp_f32_e32 v121, v121
	s_waitcnt vmcnt(8) lgkmcnt(0)
	s_barrier
	ds_read_b128 v[236:239], v206 offset:16384
	ds_read_b128 v[240:243], v206 offset:18432
	ds_read_b128 v[244:247], v206 offset:20480
	v_mfma_f32_32x32x16_bf16 v[32:47], v[224:227], v[190:193], v[32:47]
	v_exp_f32_e32 v122, v122
	v_exp_f32_e32 v123, v123
	v_mfma_f32_32x32x16_bf16 v[32:47], v[228:231], v[194:197], v[32:47]
	v_exp_f32_e32 v124, v124
	v_exp_f32_e32 v125, v125
	v_mfma_f32_32x32x16_bf16 v[32:47], v[232:235], v[252:255], v[32:47]
	v_exp_f32_e32 v126, v126
	v_exp_f32_e32 v127, v127
	s_sub_u32 s98, s98, 1
	s_cmp_lg_u32 s98, 0
	s_cbranch_scc1 .Lattn_loop
	s_waitcnt lgkmcnt(2)
	v_mfma_f32_32x32x16_bf16 v[128:143], v[236:239], v[172:175], v[16:31]
	ds_read_b128 v[190:193], v206 offset:22528
	v_cvt_pk_bf16_f32 v220, v96, v97
	v_cvt_pk_bf16_f32 v221, v98, v99
	v_cvt_pk_bf16_f32 v222, v100, v101
	s_waitcnt lgkmcnt(2)
	v_mfma_f32_32x32x16_bf16 v[128:143], v[240:243], v[168:171], v[128:143]
	ds_read_b128 v[194:197], v206 offset:24576
	v_cvt_pk_bf16_f32 v223, v102, v103
	v_add_f32_e32 v218, v96, v218
	v_add_f32_e32 v248, v97, v248
	s_waitcnt lgkmcnt(2)
	v_mfma_f32_32x32x16_bf16 v[128:143], v[244:247], v[164:167], v[128:143]
	ds_read_b128 v[252:255], v206 offset:26624
	v_add_f32_e32 v218, v98, v218
	v_add_f32_e32 v248, v99, v248
	v_add_f32_e32 v218, v100, v218
	s_waitcnt lgkmcnt(2)
	v_mfma_f32_32x32x16_bf16 v[128:143], v[190:193], v[160:163], v[128:143]
	ds_read_b128 v[236:239], v206 offset:28672
	v_add_f32_e32 v248, v101, v248
	v_add_f32_e32 v218, v102, v218
	v_add_f32_e32 v248, v103, v248
	s_waitcnt lgkmcnt(2)
	v_mfma_f32_32x32x16_bf16 v[128:143], v[194:197], v[156:159], v[128:143]
	ds_read_b128 v[240:243], v206 offset:30720
	v_cvt_pk_bf16_f32 v224, v104, v105
	v_cvt_pk_bf16_f32 v225, v106, v107
	v_cvt_pk_bf16_f32 v226, v108, v109
	s_waitcnt lgkmcnt(2)
	v_mfma_f32_32x32x16_bf16 v[128:143], v[252:255], v[152:155], v[128:143]
	ds_read_b128 v[244:247], v206 offset:17408
	v_cvt_pk_bf16_f32 v227, v110, v111
	v_add_f32_e32 v218, v104, v218
	v_add_f32_e32 v248, v105, v248
	s_waitcnt lgkmcnt(2)
	v_mfma_f32_32x32x16_bf16 v[128:143], v[236:239], v[148:151], v[128:143]
	ds_read_b128 v[190:193], v206 offset:19456
	v_add_f32_e32 v218, v106, v218
	v_add_f32_e32 v248, v107, v248
	v_add_f32_e32 v218, v108, v218
	s_waitcnt lgkmcnt(2)
	v_mfma_f32_32x32x16_bf16 v[128:143], v[240:243], v[144:147], v[128:143]
	ds_read_b128 v[194:197], v206 offset:21504
	v_add_f32_e32 v248, v109, v248
	v_add_f32_e32 v218, v110, v218
	v_add_f32_e32 v248, v111, v248
	s_waitcnt lgkmcnt(2)
	v_mfma_f32_32x32x16_bf16 v[0:15], v[244:247], v[172:175], v[16:31]
	ds_read_b128 v[252:255], v206 offset:23552
	v_cvt_pk_bf16_f32 v228, v112, v113
	v_cvt_pk_bf16_f32 v229, v114, v115
	v_cvt_pk_bf16_f32 v230, v116, v117
	s_waitcnt lgkmcnt(2)
	v_mfma_f32_32x32x16_bf16 v[0:15], v[190:193], v[168:171], v[0:15]
	ds_read_b128 v[236:239], v206 offset:25600
	v_cvt_pk_bf16_f32 v231, v118, v119
	v_add_f32_e32 v249, v112, v249
	v_add_f32_e32 v251, v113, v251
	s_waitcnt lgkmcnt(2)
	v_mfma_f32_32x32x16_bf16 v[0:15], v[194:197], v[164:167], v[0:15]
	ds_read_b128 v[240:243], v206 offset:27648
	v_add_f32_e32 v249, v114, v249
	v_add_f32_e32 v251, v115, v251
	v_add_f32_e32 v249, v116, v249
	s_waitcnt lgkmcnt(2)
	v_mfma_f32_32x32x16_bf16 v[0:15], v[252:255], v[160:163], v[0:15]
	ds_read_b128 v[244:247], v206 offset:29696
	v_add_f32_e32 v251, v117, v251
	v_add_f32_e32 v249, v118, v249
	v_add_f32_e32 v251, v119, v251
	s_waitcnt lgkmcnt(2)
	v_mfma_f32_32x32x16_bf16 v[0:15], v[236:239], v[156:159], v[0:15]
	ds_read_b128 v[190:193], v206 offset:31744
	v_cvt_pk_bf16_f32 v232, v120, v121
	v_cvt_pk_bf16_f32 v233, v122, v123
	v_cvt_pk_bf16_f32 v234, v124, v125
	s_waitcnt lgkmcnt(2)
	v_mfma_f32_32x32x16_bf16 v[0:15], v[240:243], v[152:155], v[0:15]
	ds_read_b64_tr_b16 v[194:195], v201 offset:0
	ds_read_b64_tr_b16 v[196:197], v201 offset:2048
	v_cvt_pk_bf16_f32 v235, v126, v127
	v_add_f32_e32 v249, v120, v249
	v_add_f32_e32 v251, v121, v251
	s_waitcnt lgkmcnt(3)
	v_mfma_f32_32x32x16_bf16 v[0:15], v[244:247], v[148:151], v[0:15]
	ds_read_b64_tr_b16 v[252:253], v201 offset:4096
	ds_read_b64_tr_b16 v[254:255], v201 offset:6144
	v_add_f32_e32 v249, v122, v249
	v_add_f32_e32 v251, v123, v251
	v_add_f32_e32 v249, v124, v249
	s_waitcnt lgkmcnt(4)
	v_mfma_f32_32x32x16_bf16 v[0:15], v[190:193], v[144:147], v[0:15]
	ds_read_b64_tr_b16 v[236:237], v201 offset:8192
	ds_read_b64_tr_b16 v[238:239], v201 offset:10240
	v_add_f32_e32 v251, v125, v251
	v_add_f32_e32 v249, v126, v249
	v_add_f32_e32 v251, v127, v251
	s_waitcnt vmcnt(6)
	s_barrier
	s_waitcnt lgkmcnt(4)
	v_mfma_f32_32x32x16_bf16 v[80:95], v[220:223], v[194:197], v[80:95]
	ds_read_b64_tr_b16 v[240:241], v201 offset:12288
	ds_read_b64_tr_b16 v[242:243], v201 offset:14336
	s_add_i32 m0, s68, 49152
	v_exp_f32_e32 v128, v128
	v_exp_f32_e32 v129, v129
	global_load_lds_dwordx4 v199, s[70:71]
	s_waitcnt lgkmcnt(4)
	v_mfma_f32_32x32x16_bf16 v[80:95], v[224:227], v[252:255], v[80:95]
	ds_read_b64_tr_b16 v[244:245], v201 offset:512
	ds_read_b64_tr_b16 v[246:247], v201 offset:2560
	s_add_i32 m0, s68, 57344
	v_exp_f32_e32 v130, v130
	v_exp_f32_e32 v131, v131
	global_load_lds_dwordx4 v219, s[70:71]
	s_add_u32 s70, s70, 0x90000
	s_addc_u32 s71, s71, 0
	s_waitcnt lgkmcnt(4)
	v_mfma_f32_32x32x16_bf16 v[80:95], v[228:231], v[236:239], v[80:95]
	ds_read_b64_tr_b16 v[190:191], v201 offset:4608
	ds_read_b64_tr_b16 v[192:193], v201 offset:6656
	v_exp_f32_e32 v132, v132
	v_exp_f32_e32 v133, v133
	s_waitcnt lgkmcnt(4)
	v_mfma_f32_32x32x16_bf16 v[80:95], v[232:235], v[240:243], v[80:95]
	ds_read_b64_tr_b16 v[194:195], v201 offset:8704
	ds_read_b64_tr_b16 v[196:197], v201 offset:10752
	v_exp_f32_e32 v134, v134
	v_exp_f32_e32 v135, v135
	s_waitcnt lgkmcnt(4)
	v_mfma_f32_32x32x16_bf16 v[64:79], v[220:223], v[244:247], v[64:79]
	ds_read_b64_tr_b16 v[252:253], v201 offset:12800
	ds_read_b64_tr_b16 v[254:255], v201 offset:14848
	v_exp_f32_e32 v136, v136
	v_exp_f32_e32 v137, v137
	s_waitcnt lgkmcnt(4)
	v_mfma_f32_32x32x16_bf16 v[64:79], v[224:227], v[190:193], v[64:79]
	ds_read_b64_tr_b16 v[236:237], v201 offset:1024
	ds_read_b64_tr_b16 v[238:239], v201 offset:3072
	v_exp_f32_e32 v138, v138
	v_exp_f32_e32 v139, v139
	s_waitcnt lgkmcnt(4)
	v_mfma_f32_32x32x16_bf16 v[64:79], v[228:231], v[194:197], v[64:79]
	ds_read_b64_tr_b16 v[240:241], v201 offset:5120
	ds_read_b64_tr_b16 v[242:243], v201 offset:7168
	v_exp_f32_e32 v140, v140
	v_exp_f32_e32 v141, v141
	s_waitcnt lgkmcnt(4)
	v_mfma_f32_32x32x16_bf16 v[64:79], v[232:235], v[252:255], v[64:79]
	ds_read_b64_tr_b16 v[244:245], v201 offset:9216
	ds_read_b64_tr_b16 v[246:247], v201 offset:11264
	v_exp_f32_e32 v142, v142
	v_exp_f32_e32 v143, v143
	s_waitcnt lgkmcnt(4)
	v_mfma_f32_32x32x16_bf16 v[48:63], v[220:223], v[236:239], v[48:63]
	ds_read_b64_tr_b16 v[236:237], v201 offset:13312
	ds_read_b64_tr_b16 v[238:239], v201 offset:15360
	ds_read_b64_tr_b16 v[190:191], v201 offset:5632
	ds_read_b64_tr_b16 v[192:193], v201 offset:7680
	v_exp_f32_e32 v0, v0
	v_exp_f32_e32 v1, v1
	s_waitcnt lgkmcnt(6)
	v_mfma_f32_32x32x16_bf16 v[48:63], v[224:227], v[240:243], v[48:63]
	ds_read_b64_tr_b16 v[240:241], v201 offset:1536
	ds_read_b64_tr_b16 v[242:243], v201 offset:3584
	ds_read_b64_tr_b16 v[194:195], v201 offset:9728
	ds_read_b64_tr_b16 v[196:197], v201 offset:11776
	v_exp_f32_e32 v2, v2
	v_exp_f32_e32 v3, v3
	s_waitcnt lgkmcnt(8)
	v_mfma_f32_32x32x16_bf16 v[48:63], v[228:231], v[244:247], v[48:63]
	ds_read_b64_tr_b16 v[252:253], v201 offset:13824
	ds_read_b64_tr_b16 v[254:255], v201 offset:15872
	v_exp_f32_e32 v4, v4
	v_exp_f32_e32 v5, v5
	s_waitcnt lgkmcnt(8)
	v_mfma_f32_32x32x16_bf16 v[48:63], v[232:235], v[236:239], v[48:63]
	v_exp_f32_e32 v6, v6
	v_exp_f32_e32 v7, v7
	s_waitcnt lgkmcnt(4)
	v_mfma_f32_32x32x16_bf16 v[32:47], v[220:223], v[240:243], v[32:47]
	v_exp_f32_e32 v8, v8
	v_exp_f32_e32 v9, v9
	s_waitcnt vmcnt(6) lgkmcnt(0)
	s_barrier
	ds_read_b128 v[236:239], v206 offset:32768
	ds_read_b128 v[240:243], v206 offset:34816
	ds_read_b128 v[244:247], v206 offset:36864
	v_mfma_f32_32x32x16_bf16 v[32:47], v[224:227], v[190:193], v[32:47]
	v_exp_f32_e32 v10, v10
	v_exp_f32_e32 v11, v11
	v_mfma_f32_32x32x16_bf16 v[32:47], v[228:231], v[194:197], v[32:47]
	v_exp_f32_e32 v12, v12
	v_exp_f32_e32 v13, v13
	v_mfma_f32_32x32x16_bf16 v[32:47], v[232:235], v[252:255], v[32:47]
	v_exp_f32_e32 v14, v14
	v_exp_f32_e32 v15, v15
	s_waitcnt lgkmcnt(2)
	v_mfma_f32_32x32x16_bf16 v[96:111], v[236:239], v[172:175], v[16:31]
	ds_read_b128 v[190:193], v206 offset:38912
	v_cvt_pk_bf16_f32 v220, v128, v129
	v_cvt_pk_bf16_f32 v221, v130, v131
	v_cvt_pk_bf16_f32 v222, v132, v133
	s_waitcnt lgkmcnt(2)
	v_mfma_f32_32x32x16_bf16 v[96:111], v[240:243], v[168:171], v[96:111]
	ds_read_b128 v[194:197], v206 offset:40960
	v_cvt_pk_bf16_f32 v223, v134, v135
	v_add_f32_e32 v218, v128, v218
	v_add_f32_e32 v248, v129, v248
	s_waitcnt lgkmcnt(2)
	v_mfma_f32_32x32x16_bf16 v[96:111], v[244:247], v[164:167], v[96:111]
	ds_read_b128 v[252:255], v206 offset:43008
	v_add_f32_e32 v218, v130, v218
	v_add_f32_e32 v248, v131, v248
	v_add_f32_e32 v218, v132, v218
	s_waitcnt lgkmcnt(2)
	v_mfma_f32_32x32x16_bf16 v[96:111], v[190:193], v[160:163], v[96:111]
	ds_read_b128 v[236:239], v206 offset:45056
	v_add_f32_e32 v248, v133, v248
	v_add_f32_e32 v218, v134, v218
	v_add_f32_e32 v248, v135, v248
	s_waitcnt lgkmcnt(2)
	v_mfma_f32_32x32x16_bf16 v[96:111], v[194:197], v[156:159], v[96:111]
	ds_read_b128 v[240:243], v206 offset:47104
	v_cvt_pk_bf16_f32 v224, v136, v137
	v_cvt_pk_bf16_f32 v225, v138, v139
	v_cvt_pk_bf16_f32 v226, v140, v141
	s_waitcnt lgkmcnt(2)
	v_mfma_f32_32x32x16_bf16 v[96:111], v[252:255], v[152:155], v[96:111]
	ds_read_b128 v[244:247], v206 offset:33792
	v_cvt_pk_bf16_f32 v227, v142, v143
	v_add_f32_e32 v218, v136, v218
	v_add_f32_e32 v248, v137, v248
	s_waitcnt lgkmcnt(2)
	v_mfma_f32_32x32x16_bf16 v[96:111], v[236:239], v[148:151], v[96:111]
	ds_read_b128 v[190:193], v206 offset:35840
	v_add_f32_e32 v218, v138, v218
	v_add_f32_e32 v248, v139, v248
	v_add_f32_e32 v218, v140, v218
	s_waitcnt lgkmcnt(2)
	v_mfma_f32_32x32x16_bf16 v[96:111], v[240:243], v[144:147], v[96:111]
	ds_read_b128 v[194:197], v206 offset:37888
	v_add_f32_e32 v248, v141, v248
	v_add_f32_e32 v218, v142, v218
	v_add_f32_e32 v248, v143, v248
	s_waitcnt lgkmcnt(2)
	v_mfma_f32_32x32x16_bf16 v[112:127], v[244:247], v[172:175], v[16:31]
	ds_read_b128 v[252:255], v206 offset:39936
	v_cvt_pk_bf16_f32 v228, v0, v1
	v_cvt_pk_bf16_f32 v229, v2, v3
	v_cvt_pk_bf16_f32 v230, v4, v5
	s_waitcnt lgkmcnt(2)
	v_mfma_f32_32x32x16_bf16 v[112:127], v[190:193], v[168:171], v[112:127]
	ds_read_b128 v[236:239], v206 offset:41984
	v_cvt_pk_bf16_f32 v231, v6, v7
	v_add_f32_e32 v249, v0, v249
	v_add_f32_e32 v251, v1, v251
	s_waitcnt lgkmcnt(2)
	v_mfma_f32_32x32x16_bf16 v[112:127], v[194:197], v[164:167], v[112:127]
	ds_read_b128 v[240:243], v206 offset:44032
	v_add_f32_e32 v249, v2, v249
	v_add_f32_e32 v251, v3, v251
	v_add_f32_e32 v249, v4, v249
	s_waitcnt lgkmcnt(2)
	v_mfma_f32_32x32x16_bf16 v[112:127], v[252:255], v[160:163], v[112:127]
	ds_read_b128 v[244:247], v206 offset:46080
	v_add_f32_e32 v251, v5, v251
	v_add_f32_e32 v249, v6, v249
	v_add_f32_e32 v251, v7, v251
	s_waitcnt lgkmcnt(2)
	v_mfma_f32_32x32x16_bf16 v[112:127], v[236:239], v[156:159], v[112:127]
	ds_read_b128 v[190:193], v206 offset:48128
	v_cvt_pk_bf16_f32 v232, v8, v9
	v_cvt_pk_bf16_f32 v233, v10, v11
	v_cvt_pk_bf16_f32 v234, v12, v13
	s_waitcnt lgkmcnt(2)
	v_mfma_f32_32x32x16_bf16 v[112:127], v[240:243], v[152:155], v[112:127]
	ds_read_b64_tr_b16 v[194:195], v201 offset:16384
	ds_read_b64_tr_b16 v[196:197], v201 offset:18432
	v_cvt_pk_bf16_f32 v235, v14, v15
	v_add_f32_e32 v249, v8, v249
	v_add_f32_e32 v251, v9, v251
	s_waitcnt lgkmcnt(3)
	v_mfma_f32_32x32x16_bf16 v[112:127], v[244:247], v[148:151], v[112:127]
	ds_read_b64_tr_b16 v[252:253], v201 offset:20480
	ds_read_b64_tr_b16 v[254:255], v201 offset:22528
	v_add_f32_e32 v249, v10, v249
	v_add_f32_e32 v251, v11, v251
	v_add_f32_e32 v249, v12, v249
	s_waitcnt lgkmcnt(4)
	v_mfma_f32_32x32x16_bf16 v[112:127], v[190:193], v[144:147], v[112:127]
	ds_read_b64_tr_b16 v[236:237], v201 offset:24576
	ds_read_b64_tr_b16 v[238:239], v201 offset:26624
	v_add_f32_e32 v251, v13, v251
	v_add_f32_e32 v249, v14, v249
	v_add_f32_e32 v251, v15, v251
	s_waitcnt vmcnt(4)
	s_barrier
	s_waitcnt lgkmcnt(4)
	v_mfma_f32_32x32x16_bf16 v[80:95], v[220:223], v[194:197], v[80:95]
	ds_read_b64_tr_b16 v[240:241], v201 offset:28672
	ds_read_b64_tr_b16 v[242:243], v201 offset:30720
	v_exp_f32_e32 v96, v96
	v_exp_f32_e32 v97, v97
	s_waitcnt lgkmcnt(4)
	v_mfma_f32_32x32x16_bf16 v[80:95], v[224:227], v[252:255], v[80:95]
	ds_read_b64_tr_b16 v[244:245], v201 offset:16896
	ds_read_b64_tr_b16 v[246:247], v201 offset:18944
	v_exp_f32_e32 v98, v98
	v_exp_f32_e32 v99, v99
	s_waitcnt lgkmcnt(4)
	v_mfma_f32_32x32x16_bf16 v[80:95], v[228:231], v[236:239], v[80:95]
	ds_read_b64_tr_b16 v[190:191], v201 offset:20992
	ds_read_b64_tr_b16 v[192:193], v201 offset:23040
	v_exp_f32_e32 v100, v100
	v_exp_f32_e32 v101, v101
	s_waitcnt lgkmcnt(4)
	v_mfma_f32_32x32x16_bf16 v[80:95], v[232:235], v[240:243], v[80:95]
	ds_read_b64_tr_b16 v[194:195], v201 offset:25088
	ds_read_b64_tr_b16 v[196:197], v201 offset:27136
	v_exp_f32_e32 v102, v102
	v_exp_f32_e32 v103, v103
	s_waitcnt lgkmcnt(4)
	v_mfma_f32_32x32x16_bf16 v[64:79], v[220:223], v[244:247], v[64:79]
	ds_read_b64_tr_b16 v[252:253], v201 offset:29184
	ds_read_b64_tr_b16 v[254:255], v201 offset:31232
	v_exp_f32_e32 v104, v104
	v_exp_f32_e32 v105, v105
	s_waitcnt lgkmcnt(4)
	v_mfma_f32_32x32x16_bf16 v[64:79], v[224:227], v[190:193], v[64:79]
	ds_read_b64_tr_b16 v[236:237], v201 offset:17408
	ds_read_b64_tr_b16 v[238:239], v201 offset:19456
	v_exp_f32_e32 v106, v106
	v_exp_f32_e32 v107, v107
	s_waitcnt lgkmcnt(4)
	v_mfma_f32_32x32x16_bf16 v[64:79], v[228:231], v[194:197], v[64:79]
	ds_read_b64_tr_b16 v[240:241], v201 offset:21504
	ds_read_b64_tr_b16 v[242:243], v201 offset:23552
	v_exp_f32_e32 v108, v108
	v_exp_f32_e32 v109, v109
	s_waitcnt lgkmcnt(4)
	v_mfma_f32_32x32x16_bf16 v[64:79], v[232:235], v[252:255], v[64:79]
	ds_read_b64_tr_b16 v[244:245], v201 offset:25600
	ds_read_b64_tr_b16 v[246:247], v201 offset:27648
	v_exp_f32_e32 v110, v110
	v_exp_f32_e32 v111, v111
	s_waitcnt lgkmcnt(4)
	v_mfma_f32_32x32x16_bf16 v[48:63], v[220:223], v[236:239], v[48:63]
	ds_read_b64_tr_b16 v[236:237], v201 offset:29696
	ds_read_b64_tr_b16 v[238:239], v201 offset:31744
	ds_read_b64_tr_b16 v[190:191], v201 offset:22016
	ds_read_b64_tr_b16 v[192:193], v201 offset:24064
	v_exp_f32_e32 v112, v112
	v_exp_f32_e32 v113, v113
	s_waitcnt lgkmcnt(6)
	v_mfma_f32_32x32x16_bf16 v[48:63], v[224:227], v[240:243], v[48:63]
	ds_read_b64_tr_b16 v[240:241], v201 offset:17920
	ds_read_b64_tr_b16 v[242:243], v201 offset:19968
	ds_read_b64_tr_b16 v[194:195], v201 offset:26112
	ds_read_b64_tr_b16 v[196:197], v201 offset:28160
	v_exp_f32_e32 v114, v114
	v_exp_f32_e32 v115, v115
	s_waitcnt lgkmcnt(8)
	v_mfma_f32_32x32x16_bf16 v[48:63], v[228:231], v[244:247], v[48:63]
	ds_read_b64_tr_b16 v[252:253], v201 offset:30208
	ds_read_b64_tr_b16 v[254:255], v201 offset:32256
	v_exp_f32_e32 v116, v116
	v_exp_f32_e32 v117, v117
	s_waitcnt lgkmcnt(8)
	v_mfma_f32_32x32x16_bf16 v[48:63], v[232:235], v[236:239], v[48:63]
	v_exp_f32_e32 v118, v118
	v_exp_f32_e32 v119, v119
	s_waitcnt lgkmcnt(4)
	v_mfma_f32_32x32x16_bf16 v[32:47], v[220:223], v[240:243], v[32:47]
	v_exp_f32_e32 v120, v120
	v_exp_f32_e32 v121, v121
	s_waitcnt vmcnt(2) lgkmcnt(0)
	s_barrier
	ds_read_b128 v[236:239], v206 offset:49152
	ds_read_b128 v[240:243], v206 offset:51200
	ds_read_b128 v[244:247], v206 offset:53248
	v_mfma_f32_32x32x16_bf16 v[32:47], v[224:227], v[190:193], v[32:47]
	v_exp_f32_e32 v122, v122
	v_exp_f32_e32 v123, v123
	v_mfma_f32_32x32x16_bf16 v[32:47], v[228:231], v[194:197], v[32:47]
	v_exp_f32_e32 v124, v124
	v_exp_f32_e32 v125, v125
	v_mfma_f32_32x32x16_bf16 v[32:47], v[232:235], v[252:255], v[32:47]
	v_exp_f32_e32 v126, v126
	v_exp_f32_e32 v127, v127
	s_waitcnt lgkmcnt(2)
	v_mfma_f32_32x32x16_bf16 v[128:143], v[236:239], v[172:175], v[16:31]
	ds_read_b128 v[190:193], v206 offset:55296
	v_cvt_pk_bf16_f32 v220, v96, v97
	v_cvt_pk_bf16_f32 v221, v98, v99
	v_cvt_pk_bf16_f32 v222, v100, v101
	s_waitcnt lgkmcnt(2)
	v_mfma_f32_32x32x16_bf16 v[128:143], v[240:243], v[168:171], v[128:143]
	ds_read_b128 v[194:197], v206 offset:57344
	v_cvt_pk_bf16_f32 v223, v102, v103
	v_add_f32_e32 v218, v96, v218
	v_add_f32_e32 v248, v97, v248
	s_waitcnt lgkmcnt(2)
	v_mfma_f32_32x32x16_bf16 v[128:143], v[244:247], v[164:167], v[128:143]
	ds_read_b128 v[252:255], v206 offset:59392
	v_add_f32_e32 v218, v98, v218
	v_add_f32_e32 v248, v99, v248
	v_add_f32_e32 v218, v100, v218
	s_waitcnt lgkmcnt(2)
	v_mfma_f32_32x32x16_bf16 v[128:143], v[190:193], v[160:163], v[128:143]
	ds_read_b128 v[236:239], v206 offset:61440
	v_add_f32_e32 v248, v101, v248
	v_add_f32_e32 v218, v102, v218
	v_add_f32_e32 v248, v103, v248
	s_waitcnt lgkmcnt(2)
	v_mfma_f32_32x32x16_bf16 v[128:143], v[194:197], v[156:159], v[128:143]
	ds_read_b128 v[240:243], v206 offset:63488
	v_cvt_pk_bf16_f32 v224, v104, v105
	v_cvt_pk_bf16_f32 v225, v106, v107
	v_cvt_pk_bf16_f32 v226, v108, v109
	s_waitcnt lgkmcnt(2)
	v_mfma_f32_32x32x16_bf16 v[128:143], v[252:255], v[152:155], v[128:143]
	ds_read_b128 v[244:247], v206 offset:50176
	v_cvt_pk_bf16_f32 v227, v110, v111
	v_add_f32_e32 v218, v104, v218
	v_add_f32_e32 v248, v105, v248
	s_waitcnt lgkmcnt(2)
	v_mfma_f32_32x32x16_bf16 v[128:143], v[236:239], v[148:151], v[128:143]
	ds_read_b128 v[190:193], v206 offset:52224
	v_add_f32_e32 v218, v106, v218
	v_add_f32_e32 v248, v107, v248
	v_add_f32_e32 v218, v108, v218
	s_waitcnt lgkmcnt(2)
	v_mfma_f32_32x32x16_bf16 v[128:143], v[240:243], v[144:147], v[128:143]
	ds_read_b128 v[194:197], v206 offset:54272
	v_add_f32_e32 v248, v109, v248
	v_add_f32_e32 v218, v110, v218
	v_add_f32_e32 v248, v111, v248
	s_waitcnt lgkmcnt(2)
	v_mfma_f32_32x32x16_bf16 v[0:15], v[244:247], v[172:175], v[16:31]
	ds_read_b128 v[252:255], v206 offset:56320
	v_cvt_pk_bf16_f32 v228, v112, v113
	v_cvt_pk_bf16_f32 v229, v114, v115
	v_cvt_pk_bf16_f32 v230, v116, v117
	s_waitcnt lgkmcnt(2)
	v_mfma_f32_32x32x16_bf16 v[0:15], v[190:193], v[168:171], v[0:15]
	ds_read_b128 v[236:239], v206 offset:58368
	v_cvt_pk_bf16_f32 v231, v118, v119
	v_add_f32_e32 v249, v112, v249
	v_add_f32_e32 v251, v113, v251
	s_waitcnt lgkmcnt(2)
	v_mfma_f32_32x32x16_bf16 v[0:15], v[194:197], v[164:167], v[0:15]
	ds_read_b128 v[240:243], v206 offset:60416
	v_add_f32_e32 v249, v114, v249
	v_add_f32_e32 v251, v115, v251
	v_add_f32_e32 v249, v116, v249
	s_waitcnt lgkmcnt(2)
	v_mfma_f32_32x32x16_bf16 v[0:15], v[252:255], v[160:163], v[0:15]
	ds_read_b128 v[244:247], v206 offset:62464
	v_add_f32_e32 v251, v117, v251
	v_add_f32_e32 v249, v118, v249
	v_add_f32_e32 v251, v119, v251
	s_waitcnt lgkmcnt(2)
	v_mfma_f32_32x32x16_bf16 v[0:15], v[236:239], v[156:159], v[0:15]
	ds_read_b128 v[190:193], v206 offset:64512
	v_cvt_pk_bf16_f32 v232, v120, v121
	v_cvt_pk_bf16_f32 v233, v122, v123
	v_cvt_pk_bf16_f32 v234, v124, v125
	s_waitcnt lgkmcnt(2)
	v_mfma_f32_32x32x16_bf16 v[0:15], v[240:243], v[152:155], v[0:15]
	ds_read_b64_tr_b16 v[194:195], v201 offset:32768
	ds_read_b64_tr_b16 v[196:197], v201 offset:34816
	v_cvt_pk_bf16_f32 v235, v126, v127
	v_add_f32_e32 v249, v120, v249
	v_add_f32_e32 v251, v121, v251
	s_waitcnt lgkmcnt(3)
	v_mfma_f32_32x32x16_bf16 v[0:15], v[244:247], v[148:151], v[0:15]
	ds_read_b64_tr_b16 v[252:253], v201 offset:36864
	ds_read_b64_tr_b16 v[254:255], v201 offset:38912
	v_add_f32_e32 v249, v122, v249
	v_add_f32_e32 v251, v123, v251
	v_add_f32_e32 v249, v124, v249
	s_waitcnt lgkmcnt(4)
	v_mfma_f32_32x32x16_bf16 v[0:15], v[190:193], v[144:147], v[0:15]
	ds_read_b64_tr_b16 v[236:237], v201 offset:40960
	ds_read_b64_tr_b16 v[238:239], v201 offset:43008
	v_add_f32_e32 v251, v125, v251
	v_add_f32_e32 v249, v126, v249
	v_add_f32_e32 v251, v127, v251
	s_waitcnt vmcnt(2)
	s_barrier
	s_waitcnt lgkmcnt(4)
	v_mfma_f32_32x32x16_bf16 v[80:95], v[220:223], v[194:197], v[80:95]
	ds_read_b64_tr_b16 v[240:241], v201 offset:45056
	ds_read_b64_tr_b16 v[242:243], v201 offset:47104
	v_exp_f32_e32 v128, v128
	v_exp_f32_e32 v129, v129
	s_waitcnt lgkmcnt(4)
	v_mfma_f32_32x32x16_bf16 v[80:95], v[224:227], v[252:255], v[80:95]
	ds_read_b64_tr_b16 v[244:245], v201 offset:33280
	ds_read_b64_tr_b16 v[246:247], v201 offset:35328
	v_exp_f32_e32 v130, v130
	v_exp_f32_e32 v131, v131
	s_waitcnt lgkmcnt(4)
	v_mfma_f32_32x32x16_bf16 v[80:95], v[228:231], v[236:239], v[80:95]
	ds_read_b64_tr_b16 v[190:191], v201 offset:37376
	ds_read_b64_tr_b16 v[192:193], v201 offset:39424
	v_exp_f32_e32 v132, v132
	v_exp_f32_e32 v133, v133
	s_waitcnt lgkmcnt(4)
	v_mfma_f32_32x32x16_bf16 v[80:95], v[232:235], v[240:243], v[80:95]
	ds_read_b64_tr_b16 v[194:195], v201 offset:41472
	ds_read_b64_tr_b16 v[196:197], v201 offset:43520
	v_exp_f32_e32 v134, v134
	v_exp_f32_e32 v135, v135
	s_waitcnt lgkmcnt(4)
	v_mfma_f32_32x32x16_bf16 v[64:79], v[220:223], v[244:247], v[64:79]
	ds_read_b64_tr_b16 v[252:253], v201 offset:45568
	ds_read_b64_tr_b16 v[254:255], v201 offset:47616
	v_exp_f32_e32 v136, v136
	v_exp_f32_e32 v137, v137
	s_waitcnt lgkmcnt(4)
	v_mfma_f32_32x32x16_bf16 v[64:79], v[224:227], v[190:193], v[64:79]
	ds_read_b64_tr_b16 v[236:237], v201 offset:33792
	ds_read_b64_tr_b16 v[238:239], v201 offset:35840
	v_exp_f32_e32 v138, v138
	v_exp_f32_e32 v139, v139
	s_waitcnt lgkmcnt(4)
	v_mfma_f32_32x32x16_bf16 v[64:79], v[228:231], v[194:197], v[64:79]
	ds_read_b64_tr_b16 v[240:241], v201 offset:37888
	ds_read_b64_tr_b16 v[242:243], v201 offset:39936
	v_exp_f32_e32 v140, v140
	v_exp_f32_e32 v141, v141
	s_waitcnt lgkmcnt(4)
	v_mfma_f32_32x32x16_bf16 v[64:79], v[232:235], v[252:255], v[64:79]
	ds_read_b64_tr_b16 v[244:245], v201 offset:41984
	ds_read_b64_tr_b16 v[246:247], v201 offset:44032
	v_exp_f32_e32 v142, v142
	v_exp_f32_e32 v143, v143
	s_waitcnt lgkmcnt(4)
	v_mfma_f32_32x32x16_bf16 v[48:63], v[220:223], v[236:239], v[48:63]
	ds_read_b64_tr_b16 v[236:237], v201 offset:46080
	ds_read_b64_tr_b16 v[238:239], v201 offset:48128
	ds_read_b64_tr_b16 v[190:191], v201 offset:38400
	ds_read_b64_tr_b16 v[192:193], v201 offset:40448
	v_exp_f32_e32 v0, v0
	v_exp_f32_e32 v1, v1
	s_waitcnt lgkmcnt(6)
	v_mfma_f32_32x32x16_bf16 v[48:63], v[224:227], v[240:243], v[48:63]
	ds_read_b64_tr_b16 v[240:241], v201 offset:34304
	ds_read_b64_tr_b16 v[242:243], v201 offset:36352
	ds_read_b64_tr_b16 v[194:195], v201 offset:42496
	ds_read_b64_tr_b16 v[196:197], v201 offset:44544
	v_exp_f32_e32 v2, v2
	v_exp_f32_e32 v3, v3
	s_waitcnt lgkmcnt(8)
	v_mfma_f32_32x32x16_bf16 v[48:63], v[228:231], v[244:247], v[48:63]
	ds_read_b64_tr_b16 v[252:253], v201 offset:46592
	ds_read_b64_tr_b16 v[254:255], v201 offset:48640
	v_exp_f32_e32 v4, v4
	v_exp_f32_e32 v5, v5
	s_waitcnt lgkmcnt(8)
	v_mfma_f32_32x32x16_bf16 v[48:63], v[232:235], v[236:239], v[48:63]
	v_exp_f32_e32 v6, v6
	v_exp_f32_e32 v7, v7
	s_waitcnt lgkmcnt(4)
	v_mfma_f32_32x32x16_bf16 v[32:47], v[220:223], v[240:243], v[32:47]
	v_exp_f32_e32 v8, v8
	v_exp_f32_e32 v9, v9
	s_waitcnt vmcnt(0) lgkmcnt(0)
	s_barrier
	v_mfma_f32_32x32x16_bf16 v[32:47], v[224:227], v[190:193], v[32:47]
	v_exp_f32_e32 v10, v10
	v_exp_f32_e32 v11, v11
	v_mfma_f32_32x32x16_bf16 v[32:47], v[228:231], v[194:197], v[32:47]
	v_exp_f32_e32 v12, v12
	v_exp_f32_e32 v13, v13
	v_mfma_f32_32x32x16_bf16 v[32:47], v[232:235], v[252:255], v[32:47]
	v_exp_f32_e32 v14, v14
	v_exp_f32_e32 v15, v15
	v_cvt_pk_bf16_f32 v220, v128, v129
	v_cvt_pk_bf16_f32 v221, v130, v131
	v_cvt_pk_bf16_f32 v222, v132, v133
	v_cvt_pk_bf16_f32 v223, v134, v135
	v_add_f32_e32 v218, v128, v218
	v_add_f32_e32 v248, v129, v248
	v_add_f32_e32 v218, v130, v218
	v_add_f32_e32 v248, v131, v248
	v_add_f32_e32 v218, v132, v218
	v_add_f32_e32 v248, v133, v248
	v_add_f32_e32 v218, v134, v218
	v_add_f32_e32 v248, v135, v248
	v_cvt_pk_bf16_f32 v224, v136, v137
	v_cvt_pk_bf16_f32 v225, v138, v139
	v_cvt_pk_bf16_f32 v226, v140, v141
	v_cvt_pk_bf16_f32 v227, v142, v143
	v_add_f32_e32 v218, v136, v218
	v_add_f32_e32 v248, v137, v248
	v_add_f32_e32 v218, v138, v218
	v_add_f32_e32 v248, v139, v248
	v_add_f32_e32 v218, v140, v218
	v_add_f32_e32 v248, v141, v248
	v_add_f32_e32 v218, v142, v218
	v_add_f32_e32 v248, v143, v248
	v_cvt_pk_bf16_f32 v228, v0, v1
	v_cvt_pk_bf16_f32 v229, v2, v3
	v_cvt_pk_bf16_f32 v230, v4, v5
	v_cvt_pk_bf16_f32 v231, v6, v7
	v_add_f32_e32 v249, v0, v249
	v_add_f32_e32 v251, v1, v251
	v_add_f32_e32 v249, v2, v249
	v_add_f32_e32 v251, v3, v251
	v_add_f32_e32 v249, v4, v249
	v_add_f32_e32 v251, v5, v251
	v_add_f32_e32 v249, v6, v249
	v_add_f32_e32 v251, v7, v251
	v_cvt_pk_bf16_f32 v232, v8, v9
	v_cvt_pk_bf16_f32 v233, v10, v11
	v_cvt_pk_bf16_f32 v234, v12, v13
	v_cvt_pk_bf16_f32 v235, v14, v15
	v_add_f32_e32 v249, v8, v249
	v_add_f32_e32 v251, v9, v251
	v_add_f32_e32 v249, v10, v249
	v_add_f32_e32 v251, v11, v251
	v_add_f32_e32 v249, v12, v249
	v_add_f32_e32 v251, v13, v251
	v_add_f32_e32 v249, v14, v249
	v_add_f32_e32 v251, v15, v251
	s_waitcnt vmcnt(0)
	s_barrier
	ds_read_b64_tr_b16 v[194:195], v201 offset:49152
	ds_read_b64_tr_b16 v[196:197], v201 offset:51200
	ds_read_b64_tr_b16 v[252:253], v201 offset:53248
	ds_read_b64_tr_b16 v[254:255], v201 offset:55296
	ds_read_b64_tr_b16 v[236:237], v201 offset:57344
	ds_read_b64_tr_b16 v[238:239], v201 offset:59392
	s_nop 1
	s_waitcnt lgkmcnt(4)
	v_mfma_f32_32x32x16_bf16 v[80:95], v[220:223], v[194:197], v[80:95]
	ds_read_b64_tr_b16 v[240:241], v201 offset:61440
	ds_read_b64_tr_b16 v[242:243], v201 offset:63488
	s_waitcnt lgkmcnt(4)
	v_mfma_f32_32x32x16_bf16 v[80:95], v[224:227], v[252:255], v[80:95]
	ds_read_b64_tr_b16 v[244:245], v201 offset:49664
	ds_read_b64_tr_b16 v[246:247], v201 offset:51712
	s_waitcnt lgkmcnt(4)
	v_mfma_f32_32x32x16_bf16 v[80:95], v[228:231], v[236:239], v[80:95]
	ds_read_b64_tr_b16 v[190:191], v201 offset:53760
	ds_read_b64_tr_b16 v[192:193], v201 offset:55808
	s_waitcnt lgkmcnt(4)
	v_mfma_f32_32x32x16_bf16 v[80:95], v[232:235], v[240:243], v[80:95]
	ds_read_b64_tr_b16 v[194:195], v201 offset:57856
	ds_read_b64_tr_b16 v[196:197], v201 offset:59904
	s_waitcnt lgkmcnt(4)
	v_mfma_f32_32x32x16_bf16 v[64:79], v[220:223], v[244:247], v[64:79]
	ds_read_b64_tr_b16 v[252:253], v201 offset:61952
	ds_read_b64_tr_b16 v[254:255], v201 offset:64000
	s_waitcnt lgkmcnt(4)
	v_mfma_f32_32x32x16_bf16 v[64:79], v[224:227], v[190:193], v[64:79]
	ds_read_b64_tr_b16 v[236:237], v201 offset:50176
	ds_read_b64_tr_b16 v[238:239], v201 offset:52224
	s_waitcnt lgkmcnt(4)
	v_mfma_f32_32x32x16_bf16 v[64:79], v[228:231], v[194:197], v[64:79]
	ds_read_b64_tr_b16 v[240:241], v201 offset:54272
	ds_read_b64_tr_b16 v[242:243], v201 offset:56320
	s_waitcnt lgkmcnt(4)
	v_mfma_f32_32x32x16_bf16 v[64:79], v[232:235], v[252:255], v[64:79]
	ds_read_b64_tr_b16 v[244:245], v201 offset:58368
	ds_read_b64_tr_b16 v[246:247], v201 offset:60416
	s_waitcnt lgkmcnt(4)
	v_mfma_f32_32x32x16_bf16 v[48:63], v[220:223], v[236:239], v[48:63]
	ds_read_b64_tr_b16 v[236:237], v201 offset:62464
	ds_read_b64_tr_b16 v[238:239], v201 offset:64512
	ds_read_b64_tr_b16 v[190:191], v201 offset:54784
	ds_read_b64_tr_b16 v[192:193], v201 offset:56832
	s_waitcnt lgkmcnt(6)
	v_mfma_f32_32x32x16_bf16 v[48:63], v[224:227], v[240:243], v[48:63]
	ds_read_b64_tr_b16 v[240:241], v201 offset:50688
	ds_read_b64_tr_b16 v[242:243], v201 offset:52736
	ds_read_b64_tr_b16 v[194:195], v201 offset:58880
	ds_read_b64_tr_b16 v[196:197], v201 offset:60928
	s_waitcnt lgkmcnt(8)
	v_mfma_f32_32x32x16_bf16 v[48:63], v[228:231], v[244:247], v[48:63]
	ds_read_b64_tr_b16 v[252:253], v201 offset:62976
	ds_read_b64_tr_b16 v[254:255], v201 offset:65024
	s_waitcnt lgkmcnt(8)
	v_mfma_f32_32x32x16_bf16 v[48:63], v[232:235], v[236:239], v[48:63]
	s_waitcnt lgkmcnt(4)
	v_mfma_f32_32x32x16_bf16 v[32:47], v[220:223], v[240:243], v[32:47]
	v_mfma_f32_32x32x16_bf16 v[32:47], v[224:227], v[190:193], v[32:47]
	s_waitcnt lgkmcnt(2)
	v_mfma_f32_32x32x16_bf16 v[32:47], v[228:231], v[194:197], v[32:47]
	s_waitcnt lgkmcnt(0)
	v_mfma_f32_32x32x16_bf16 v[32:47], v[232:235], v[252:255], v[32:47]
	s_cmp_gt_u32 s33, 3
	s_cbranch_scc1 .Lattn_lag_out
	s_barrier
.Lattn_lag_out:
	v_add_f32_e32 v218, v218, v248
	v_add_f32_e32 v249, v249, v251
	s_and_b32 s0, s97, 0x3fffffc0
	s_lshl_b32 s0, s0, 2
	v_add_f32_e32 v236, v218, v249
	s_add_i32 s33, s0, 0x20010
	v_mov_b32_e32 v237, v236
	v_lshl_add_u32 v240, v178, 2, s33
	s_nop 1
	v_permlane32_swap_b32_e32 v236, v237
	v_mov_b32_e32 v0, 0
	v_mov_b32_e32 v1, 0
	v_mov_b32_e32 v2, 0
	v_mov_b32_e32 v3, 0
	v_mov_b32_e32 v4, 0
	v_mov_b32_e32 v5, 0
	v_mov_b32_e32 v6, 0
	v_mov_b32_e32 v7, 0
	v_mov_b32_e32 v8, 0
	v_mov_b32_e32 v9, 0
	v_mov_b32_e32 v10, 0
	v_mov_b32_e32 v11, 0
	v_mov_b32_e32 v12, 0
	v_mov_b32_e32 v13, 0
	v_mov_b32_e32 v14, 0
	v_mov_b32_e32 v15, 0
	v_add_f32_e32 v236, v236, v237
	s_setprio 0
	s_and_saveexec_b64 s[0:1], vcc
	ds_write_b32 v240, v236
	s_branch .LBB0_236

.LBB0_485:
	s_cmp_lt_i32 s54, 6
	s_cselect_b64 s[4:5], -1, 0
	s_and_b64 s[0:1], s[4:5], s[0:1]
	s_andn2_b64 vcc, exec, s[0:1]
	s_cbranch_vccnz .LBB0_491
	s_cmpk_gt_i32 s56, 0x7ff
	s_cbranch_scc1 .LBB0_491
	v_mbcnt_lo_u32_b32 v0, -1, 0
	v_mbcnt_hi_u32_b32 v0, -1, v0
	v_and_b32_e32 v1, 64, v0
	v_add_u32_e32 v1, 64, v1
	v_xor_b32_e32 v2, 1, v0
	v_cmp_lt_i32_e32 vcc, v2, v1
	s_add_u32 s6, s52, 0x1f00000
	v_readlane_b32 s1, v250, 0
	v_cndmask_b32_e32 v2, v0, v2, vcc
	v_lshlrev_b32_e32 v37, 2, v2
	v_xor_b32_e32 v2, 2, v0
	v_cmp_lt_i32_e32 vcc, v2, v1
	s_addc_u32 s7, s53, 0
	v_mov_b32_e32 v29, 0
	v_cndmask_b32_e32 v2, v0, v2, vcc
	v_lshlrev_b32_e32 v41, 2, v2
	v_xor_b32_e32 v2, 4, v0
	v_cmp_lt_i32_e32 vcc, v2, v1
	v_lshlrev_b32_e32 v28, 4, v176
	s_lshl_b32 s0, s2, 6
	v_cndmask_b32_e32 v2, v0, v2, vcc
	v_lshlrev_b32_e32 v84, 2, v2
	v_xor_b32_e32 v2, 8, v0
	v_cmp_lt_i32_e32 vcc, v2, v1
	s_lshl_b32 s1, s1, 3
	v_lshl_add_u64 v[30:31], s[44:45], 0, v[28:29]
	v_cndmask_b32_e32 v2, v0, v2, vcc
	v_lshlrev_b32_e32 v85, 2, v2
	v_xor_b32_e32 v2, 16, v0
	v_cmp_lt_i32_e32 vcc, v2, v1
	s_waitcnt vmcnt(2)
	v_lshl_add_u64 v[32:33], s[46:47], 0, v[28:29]
	v_lshl_add_u64 v[34:35], s[6:7], 0, v[28:29]
	v_cndmask_b32_e32 v2, v0, v2, vcc
	v_lshlrev_b32_e32 v86, 2, v2
	v_xor_b32_e32 v2, 32, v0
	v_cmp_lt_i32_e32 vcc, v2, v1
	v_lshlrev_b32_e32 v36, 3, v176
	s_add_i32 s8, s0, s1
	v_cndmask_b32_e32 v0, v0, v2, vcc
	v_lshlrev_b32_e32 v87, 2, v0
	s_lshl_b32 s15, s34, 6
	v_lshlrev_b32_e32 v38, 4, v176
	v_mov_b32_e32 v39, v29
	s_mov_b64 s[12:13], 0x1000
	s_movk_i32 s20, 0x1000
	s_mov_b32 s14, 0x3a800000
	s_mov_b32 s21, 0x800000
	s_mov_b32 s22, 0x6000000
	s_brev_b32 s23, 64
	s_mov_b32 s24, 0x6001000
	s_mov_b32 s25, 0x6002000
	s_mov_b64 s[18:19], 0x2400
	v_mov_b32_e32 v40, 0x358637bd
	global_load_dwordx4 v[188:191], v[30:31], off
	global_load_dwordx4 v[192:195], v[32:33], off
	global_load_dwordx4 v[196:199], v[30:31], off offset:1024
	global_load_dwordx4 v[200:203], v[32:33], off offset:1024
	global_load_dwordx4 v[204:207], v[30:31], off offset:2048
	global_load_dwordx4 v[208:211], v[32:33], off offset:2048
	global_load_dwordx4 v[212:215], v[30:31], off offset:3072
	global_load_dwordx4 v[216:219], v[32:33], off offset:3072

.LBB0_489:
	v_lshl_add_u64 v[16:17], s[52:53], 0, v[42:43]
	v_add_co_u32_e64 v72, s[0:1], s22, v16
	v_lshl_add_u64 v[18:19], s[52:53], 0, v[44:45]
	s_nop 0
	v_addc_co_u32_e64 v73, s[0:1], 0, v17, s[0:1]
	v_lshl_add_u64 v[70:71], s[52:53], 0, v[46:47]
	v_add_co_u32_e64 v64, s[0:1], s23, v18
	v_add_co_u32_e32 v74, vcc, 0xf000000, v70
	s_nop 0
	v_addc_co_u32_e64 v65, s[0:1], 0, v19, s[0:1]
	v_add_co_u32_e64 v66, s[0:1], s24, v16
	v_addc_co_u32_e32 v75, vcc, 0, v71, vcc
	s_nop 0
	v_addc_co_u32_e64 v67, s[0:1], 0, v17, s[0:1]
	v_add_co_u32_e32 v104, vcc, 0x13000000, v70
	v_add_co_u32_e64 v68, s[0:1], s25, v16
	global_load_dwordx2 v[82:83], v[72:73], off offset:3072 nt
	v_addc_co_u32_e32 v105, vcc, 0, v71, vcc
	v_addc_co_u32_e64 v69, s[0:1], 0, v17, s[0:1]
	global_load_dwordx4 v[88:91], v[74:75], off nt
	global_load_dwordx4 v[92:95], v[74:75], off offset:1024 nt
	global_load_dwordx4 v[16:19], v[74:75], off offset:3072 nt
	global_load_dwordx4 v[24:27], v[74:75], off offset:2048 nt
	v_add_co_u32_e32 v70, vcc, 0x17000000, v70
	global_load_dwordx4 v[74:77], v[104:105], off nt
	global_load_dwordx4 v[78:81], v[104:105], off offset:1024 nt
	global_load_dwordx4 v[96:99], v[104:105], off offset:2048 nt
	global_load_dwordx4 v[100:103], v[104:105], off offset:3072 nt
	v_addc_co_u32_e32 v71, vcc, 0, v71, vcc
	global_load_dwordx4 v[104:107], v[70:71], off nt
	global_load_dwordx4 v[108:111], v[70:71], off offset:1024 nt
	global_load_dwordx4 v[112:115], v[70:71], off offset:2048 nt
	global_load_dwordx4 v[116:119], v[70:71], off offset:3072 nt
	global_load_dwordx2 v[220:221], v[66:67], off offset:3072 nt
	global_load_dwordx2 v[222:223], v[72:73], off offset:3584 nt
	global_load_dwordx2 v[224:225], v[66:67], off offset:3584 nt
	global_load_dwordx2 v[226:227], v[68:69], off offset:-4096 nt
	global_load_dwordx2 v[228:229], v[68:69], off nt
	global_load_dwordx2 v[230:231], v[66:67], off offset:512 nt
	global_load_dwordx2 v[232:233], v[68:69], off offset:512 nt
	s_add_i32 s9, s9, -1
	v_lshl_add_u64 v[44:45], v[44:45], 0, s[12:13]
	v_lshl_add_u64 v[42:43], v[42:43], 0, s[18:19]
	v_lshl_add_u64 v[46:47], v[46:47], 0, s[12:13]
	s_cmp_eq_u32 s9, 0
	s_waitcnt vmcnt(19)
	v_lshlrev_b32_e32 v29, 16, v82
	v_and_b32_e32 v176, 0xffff0000, v82
	v_lshlrev_b32_e32 v178, 16, v83
	v_and_b32_e32 v179, 0xffff0000, v83
	s_waitcnt vmcnt(18)
	v_pk_mul_f32 v[70:71], v[90:91], v[90:91]
	v_pk_mul_f32 v[82:83], v[88:89], v[88:89]
	s_waitcnt vmcnt(17)
	v_pk_mul_f32 v[120:121], v[94:95], v[94:95]
	v_pk_mul_f32 v[122:123], v[92:93], v[92:93]
	s_waitcnt vmcnt(15)
	v_mul_f32_e32 v124, v25, v25
	v_mul_f32_e32 v126, v27, v27
	v_mul_f32_e32 v129, 0xbfb8aa3b, v29
	v_mul_f32_e32 v131, 0xbfb8aa3b, v176
	v_mul_f32_e32 v133, 0xbfb8aa3b, v178
	v_mul_f32_e32 v135, 0xbfb8aa3b, v179
	v_mul_f32_e32 v182, v18, v18
	v_mul_f32_e32 v183, v19, v19
	s_waitcnt vmcnt(14)
	v_lshlrev_b32_e32 v128, 16, v74
	v_and_b32_e32 v74, 0xffff0000, v74
	v_lshlrev_b32_e32 v130, 16, v75
	v_and_b32_e32 v132, 0xffff0000, v75
	v_lshlrev_b32_e32 v134, 16, v76
	v_and_b32_e32 v76, 0xffff0000, v76
	v_lshlrev_b32_e32 v136, 16, v77
	v_and_b32_e32 v138, 0xffff0000, v77
	v_pk_mov_b32 v[140:141], v[82:83], v[70:71] op_sel:[1,0]
	v_mov_b32_e32 v83, v71
	s_waitcnt vmcnt(13)
	v_lshlrev_b32_e32 v70, 16, v78
	v_and_b32_e32 v78, 0xffff0000, v78
	v_lshlrev_b32_e32 v142, 16, v79
	v_and_b32_e32 v144, 0xffff0000, v79
	v_lshlrev_b32_e32 v146, 16, v80
	v_and_b32_e32 v80, 0xffff0000, v80
	v_lshlrev_b32_e32 v148, 16, v81
	v_and_b32_e32 v150, 0xffff0000, v81
	v_pk_mov_b32 v[152:153], v[122:123], v[120:121] op_sel:[1,0]
	v_mov_b32_e32 v123, v121
	s_waitcnt vmcnt(12)
	v_lshlrev_b32_e32 v120, 16, v96
	v_and_b32_e32 v96, 0xffff0000, v96
	v_lshlrev_b32_e32 v154, 16, v97
	v_and_b32_e32 v156, 0xffff0000, v97
	v_pk_fma_f32 v[124:125], v[24:25], v[24:25], v[124:125] op_sel_hi:[1,1,0]
	v_pk_fma_f32 v[126:127], v[26:27], v[26:27], v[126:127] op_sel_hi:[1,1,0]
	v_exp_f32_e32 v184, v129
	v_exp_f32_e32 v185, v131
	v_exp_f32_e32 v186, v133
	v_exp_f32_e32 v187, v135
	s_waitcnt vmcnt(10)
	v_lshlrev_b32_e32 v129, 16, v104
	v_and_b32_e32 v75, 0xffff0000, v104
	v_lshlrev_b32_e32 v131, 16, v105
	v_and_b32_e32 v133, 0xffff0000, v105
	v_lshlrev_b32_e32 v135, 16, v106
	v_and_b32_e32 v77, 0xffff0000, v106
	v_lshlrev_b32_e32 v137, 16, v107
	v_and_b32_e32 v139, 0xffff0000, v107
	s_waitcnt vmcnt(9)
	v_lshlrev_b32_e32 v71, 16, v108
	v_and_b32_e32 v79, 0xffff0000, v108
	v_lshlrev_b32_e32 v143, 16, v109
	v_and_b32_e32 v145, 0xffff0000, v109
	v_lshlrev_b32_e32 v147, 16, v110
	v_and_b32_e32 v81, 0xffff0000, v110
	v_lshlrev_b32_e32 v149, 16, v111
	v_and_b32_e32 v151, 0xffff0000, v111
	s_waitcnt vmcnt(8)
	v_lshlrev_b32_e32 v121, 16, v112
	v_and_b32_e32 v97, 0xffff0000, v112
	v_lshlrev_b32_e32 v155, 16, v113
	v_and_b32_e32 v157, 0xffff0000, v113
	v_lshlrev_b32_e32 v158, 16, v98
	v_and_b32_e32 v98, 0xffff0000, v98
	v_lshlrev_b32_e32 v160, 16, v99
	v_and_b32_e32 v162, 0xffff0000, v99
	v_lshlrev_b32_e32 v170, 16, v102
	v_and_b32_e32 v102, 0xffff0000, v102
	v_lshlrev_b32_e32 v172, 16, v103
	v_and_b32_e32 v174, 0xffff0000, v103
	v_pk_add_f32 v[82:83], v[82:83], v[140:141]
	v_pk_add_f32 v[104:105], v[122:123], v[152:153]
	v_lshlrev_b32_e32 v159, 16, v114
	v_and_b32_e32 v99, 0xffff0000, v114
	v_lshlrev_b32_e32 v161, 16, v115
	v_and_b32_e32 v163, 0xffff0000, v115
	s_waitcnt vmcnt(7)
	v_lshlrev_b32_e32 v171, 16, v118
	v_and_b32_e32 v103, 0xffff0000, v118
	v_lshlrev_b32_e32 v173, 16, v119
	v_and_b32_e32 v175, 0xffff0000, v119
	v_mov_b32_e32 v125, v183
	v_mov_b32_e32 v127, v182
	v_pk_fma_f32 v[74:75], v[50:51], v[74:75], v[128:129]
	v_pk_fma_f32 v[106:107], v[0:1], v[132:133], v[130:131]
	v_pk_fma_f32 v[76:77], v[48:49], v[76:77], v[134:135]
	v_pk_fma_f32 v[108:109], v[2:3], v[138:139], v[136:137]
	v_pk_fma_f32 v[70:71], v[54:55], v[78:79], v[70:71]
	v_pk_fma_f32 v[78:79], v[4:5], v[144:145], v[142:143]
	v_pk_fma_f32 v[80:81], v[52:53], v[80:81], v[146:147]
	v_pk_fma_f32 v[110:111], v[6:7], v[150:151], v[148:149]
	v_pk_fma_f32 v[96:97], v[58:59], v[96:97], v[120:121]
	v_pk_fma_f32 v[112:113], v[8:9], v[156:157], v[154:155]
	v_mul_f32_e32 v180, v16, v16
	v_mul_f32_e32 v181, v17, v17
	v_lshlrev_b32_e32 v164, 16, v100
	v_and_b32_e32 v100, 0xffff0000, v100
	v_lshlrev_b32_e32 v166, 16, v101
	v_and_b32_e32 v168, 0xffff0000, v101
	v_lshlrev_b32_e32 v165, 16, v116
	v_and_b32_e32 v101, 0xffff0000, v116
	v_lshlrev_b32_e32 v167, 16, v117
	v_and_b32_e32 v169, 0xffff0000, v117
	v_pk_fma_f32 v[98:99], v[56:57], v[98:99], v[158:159]
	v_pk_fma_f32 v[114:115], v[10:11], v[162:163], v[160:161]
	v_pk_fma_f32 v[102:103], v[60:61], v[102:103], v[170:171]
	v_pk_fma_f32 v[118:119], v[14:15], v[174:175], v[172:173]
	v_pk_add_f32 v[120:121], v[82:83], v[82:83] op_sel:[0,1] op_sel_hi:[1,0]
	v_pk_add_f32 v[104:105], v[104:105], v[104:105] op_sel:[0,1] op_sel_hi:[1,0]
	v_pk_add_f32 v[122:123], v[124:125], v[126:127]
	v_pk_add_f32 v[124:125], v[74:75], v[74:75] op_sel:[0,1] op_sel_hi:[1,0]
	v_pk_add_f32 v[106:107], v[106:107], v[106:107] op_sel:[0,1] op_sel_hi:[1,0]
	v_pk_add_f32 v[126:127], v[76:77], v[76:77] op_sel:[0,1] op_sel_hi:[1,0]
	v_pk_add_f32 v[108:109], v[108:109], v[108:109] op_sel:[0,1] op_sel_hi:[1,0]
	v_pk_add_f32 v[128:129], v[70:71], v[70:71] op_sel:[0,1] op_sel_hi:[1,0]
	v_pk_add_f32 v[130:131], v[78:79], v[78:79] op_sel:[0,1] op_sel_hi:[1,0]
	v_pk_add_f32 v[132:133], v[80:81], v[80:81] op_sel:[0,1] op_sel_hi:[1,0]
	v_pk_add_f32 v[110:111], v[110:111], v[110:111] op_sel:[0,1] op_sel_hi:[1,0]
	v_mov_b32_e32 v76, v96
	v_mov_b32_e32 v77, v112
	v_mov_b32_e32 v112, v97
	v_pk_fma_f32 v[100:101], v[62:63], v[100:101], v[164:165]
	v_pk_fma_f32 v[116:117], v[12:13], v[168:169], v[166:167]
	v_mov_b32_e32 v78, v114
	v_mov_b32_e32 v79, v98
	v_mov_b32_e32 v98, v115
	v_pk_add_f32 v[70:71], v[102:103], v[102:103] op_sel:[0,1] op_sel_hi:[1,0]
	v_pk_add_f32 v[74:75], v[118:119], v[118:119] op_sel:[0,1] op_sel_hi:[1,0]
	v_mov_b32_e32 v121, v180
	v_mov_b32_e32 v105, v181
	v_pk_mul_f32 v[96:97], v[124:125], v[124:125]
	v_pk_mul_f32 v[102:103], v[106:107], v[106:107]
	v_pk_mul_f32 v[114:115], v[126:127], v[126:127]
	v_pk_mul_f32 v[118:119], v[108:109], v[108:109]
	v_pk_mul_f32 v[134:135], v[128:129], v[128:129]
	v_pk_mul_f32 v[136:137], v[130:131], v[130:131]
	v_pk_mul_f32 v[138:139], v[132:133], v[132:133]
	v_pk_mul_f32 v[140:141], v[110:111], v[110:111]
	v_pk_add_f32 v[82:83], v[76:77], v[112:113]
	v_pk_add_f32 v[80:81], v[78:79], v[98:99]
	v_pk_add_f32 v[76:77], v[120:121], v[104:105]
	v_pk_mul_f32 v[104:105], v[74:75], v[74:75]
	v_add_f32_e32 v79, 1.0, v186
	v_mul_f32_e32 v78, v83, v83
	v_mov_b32_e32 v97, v100
	v_mov_b32_e32 v103, v101
	v_mov_b32_e32 v119, v100
	v_mov_b32_e32 v115, v101
	v_mov_b32_e32 v135, v116
	v_mov_b32_e32 v137, v117
	v_mov_b32_e32 v141, v116
	v_mov_b32_e32 v139, v117
	v_mul_f32_e32 v112, v81, v81
	v_pk_add_f32 v[120:121], v[76:77], v[122:123]
	v_rcp_f32_e32 v105, v79
	v_pk_fma_f32 v[100:101], v[82:83], v[82:83], v[78:79] op_sel_hi:[1,1,0]
	v_pk_add_f32 v[76:77], v[96:97], v[102:103]
	v_pk_add_f32 v[96:97], v[118:119], v[114:115]
	v_pk_add_f32 v[78:79], v[134:135], v[136:137]
	v_pk_add_f32 v[102:103], v[140:141], v[138:139]
	v_pk_mul_f32 v[98:99], v[70:71], v[70:71]
	v_pk_fma_f32 v[112:113], v[80:81], v[80:81], v[112:113] op_sel_hi:[1,1,0]
	v_pk_add_f32 v[114:115], v[76:77], v[96:97]
	v_pk_mul_f32 v[96:97], v[76:77], v[96:97]
	v_pk_add_f32 v[116:117], v[78:79], v[102:103]
	v_pk_mul_f32 v[102:103], v[78:79], v[102:103]
	v_mov_b32_e32 v101, v104
	v_mov_b32_e32 v113, v98
	v_mov_b32_e32 v115, v97
	v_mov_b32_e32 v117, v103
	v_pk_add_f32 v[96:97], v[100:101], v[112:113]
	v_pk_add_f32 v[100:101], v[114:115], v[116:117]
	v_add_f32_e32 v99, 1.0, v187
	v_pk_add_f32 v[96:97], v[100:101], v[96:97]
	v_rcp_f32_e32 v107, v99
	v_mov_b32_e32 v99, v120
	v_mov_b32_e32 v98, v96
	v_mov_b32_e32 v120, v97
	v_pk_add_f32 v[96:97], v[98:99], v[120:121]
	ds_bpermute_b32 v99, v37, v97
	ds_bpermute_b32 v98, v37, v96
	v_add_f32_e32 v71, 1.0, v184
	v_add_f32_e32 v75, 1.0, v185
	v_rcp_f32_e32 v71, v71
	v_rcp_f32_e32 v75, v75
	s_waitcnt lgkmcnt(0)
	v_pk_add_f32 v[96:97], v[96:97], v[98:99]
	ds_bpermute_b32 v99, v41, v97
	ds_bpermute_b32 v98, v41, v96
	s_waitcnt lgkmcnt(0)
	v_pk_add_f32 v[96:97], v[96:97], v[98:99]
	ds_bpermute_b32 v99, v84, v97
	ds_bpermute_b32 v98, v84, v96
	s_waitcnt lgkmcnt(0)
	v_pk_add_f32 v[96:97], v[96:97], v[98:99]
	ds_bpermute_b32 v99, v85, v97
	ds_bpermute_b32 v98, v85, v96
	s_waitcnt lgkmcnt(0)
	v_pk_add_f32 v[96:97], v[96:97], v[98:99]
	ds_bpermute_b32 v99, v86, v97
	ds_bpermute_b32 v98, v86, v96
	s_waitcnt lgkmcnt(0)
	v_pk_add_f32 v[96:97], v[96:97], v[98:99]
	ds_bpermute_b32 v99, v87, v97
	ds_bpermute_b32 v98, v87, v96
	s_waitcnt lgkmcnt(0)
	v_pk_add_f32 v[96:97], v[96:97], v[98:99]
	s_nop 0
	v_pk_fma_f32 v[96:97], v[96:97], s[14:15], v[40:41] op_sel_hi:[1,0,0]
	s_nop 0
	v_mul_f32_e32 v76, 0x4b800000, v97
	v_cmp_gt_f32_e64 s[0:1], s21, v97
	v_mul_f32_e32 v78, 0x4b800000, v96
	v_cmp_gt_f32_e32 vcc, s21, v96
	v_cndmask_b32_e64 v76, v97, v76, s[0:1]
	v_rsq_f32_e32 v76, v76
	v_cndmask_b32_e32 v78, v96, v78, vcc
	v_rsq_f32_e32 v78, v78
	v_mul_f32_e32 v96, 0x45800000, v76
	v_cndmask_b32_e64 v76, v76, v96, s[0:1]
	v_mul_f32_e32 v88, v88, v76
	v_mul_f32_e32 v89, v89, v76
	v_mul_f32_e32 v90, v90, v76
	v_mul_f32_e32 v91, v91, v76
	v_mul_f32_e32 v20, v188, v88
	v_mul_f32_e32 v21, v189, v89
	v_mul_f32_e32 v22, v190, v90
	v_mul_f32_e32 v23, v191, v91
	v_mul_f32_e32 v20, v20, v29
	v_mul_f32_e32 v21, v21, v176
	v_mul_f32_e32 v97, 0x45800000, v78
	v_mul_f32_e32 v22, v22, v178
	v_mul_f32_e32 v23, v23, v179
	v_mul_f32_e32 v20, v20, v71
	v_mul_f32_e32 v21, v21, v75
	v_cndmask_b32_e32 v78, v78, v97, vcc
	v_mul_f32_e32 v22, v22, v105
	v_mul_f32_e32 v23, v23, v107
	v_cvt_pk_bf16_f32 v20, v20, v21
	v_cvt_pk_bf16_f32 v21, v22, v23
	global_store_dwordx2 v[64:65], v[20:21], off
	v_mul_f32_e32 v97, v106, v78
	v_mul_f32_e32 v104, v24, v76
	v_mul_f32_e32 v106, v25, v76
	v_mul_f32_e32 v96, v124, v78
	v_mul_f32_e32 v98, v126, v78
	v_mul_f32_e32 v99, v108, v78
	v_mul_f32_e32 v92, v92, v76
	v_mul_f32_e32 v93, v93, v76
	v_mul_f32_e32 v94, v94, v76
	v_mul_f32_e32 v95, v95, v76
	v_mul_f32_e32 v100, v128, v78
	v_mul_f32_e32 v101, v130, v78
	v_mul_f32_e32 v102, v132, v78
	v_mul_f32_e32 v103, v110, v78
	v_mul_f32_e32 v26, v26, v76
	v_mul_f32_e32 v27, v27, v76
	v_mul_f32_e32 v16, v16, v76
	v_mul_f32_e32 v17, v17, v76
	v_mul_f32_e32 v18, v18, v76
	v_mul_f32_e32 v19, v19, v76
	s_waitcnt vmcnt(7)
	v_lshlrev_b32_e32 v29, 16, v220
	v_and_b32_e32 v24, 0xffff0000, v220
	s_waitcnt vmcnt(7)
	v_mul_f32_e32 v20, v192, v96
	v_mul_f32_e32 v21, v193, v97
	v_lshlrev_b32_e32 v71, 16, v221
	v_and_b32_e32 v25, 0xffff0000, v221
	v_mul_f32_e32 v22, v194, v98
	v_mul_f32_e32 v23, v195, v99
	v_mul_f32_e32 v20, v20, v29
	v_mul_f32_e32 v29, 0xbfb8aa3b, v29
	v_mul_f32_e32 v21, v21, v24
	v_mul_f32_e32 v24, 0xbfb8aa3b, v24
	v_mul_f32_e32 v22, v22, v71
	v_mul_f32_e32 v71, 0xbfb8aa3b, v71
	v_mul_f32_e32 v23, v23, v25
	v_mul_f32_e32 v25, 0xbfb8aa3b, v25
	v_exp_f32_e32 v29, v29
	v_exp_f32_e32 v24, v24
	v_exp_f32_e32 v71, v71
	v_exp_f32_e32 v25, v25
	v_add_f32_e32 v29, 1.0, v29
	v_add_f32_e32 v24, 1.0, v24
	v_add_f32_e32 v71, 1.0, v71
	v_add_f32_e32 v25, 1.0, v25
	v_rcp_f32_e32 v29, v29
	v_rcp_f32_e32 v24, v24
	v_rcp_f32_e32 v71, v71
	v_rcp_f32_e32 v25, v25
	v_mul_f32_e32 v20, v29, v20
	v_mul_f32_e32 v21, v24, v21
	v_mul_f32_e32 v22, v71, v22
	v_mul_f32_e32 v23, v25, v23
	v_cvt_pk_bf16_f32 v20, v20, v21
	v_cvt_pk_bf16_f32 v21, v22, v23
	global_store_dwordx2 v[64:65], v[20:21], off offset:2048
	s_nop 0
	s_waitcnt vmcnt(7)
	v_lshlrev_b32_e32 v29, 16, v222
	v_and_b32_e32 v24, 0xffff0000, v222
	s_waitcnt vmcnt(7)
	v_mul_f32_e32 v20, v92, v196
	v_mul_f32_e32 v21, v93, v197
	v_lshlrev_b32_e32 v71, 16, v223
	v_and_b32_e32 v25, 0xffff0000, v223
	v_mul_f32_e32 v22, v94, v198
	v_mul_f32_e32 v23, v95, v199
	v_mul_f32_e32 v20, v20, v29
	v_mul_f32_e32 v29, 0xbfb8aa3b, v29
	v_mul_f32_e32 v21, v21, v24
	v_mul_f32_e32 v24, 0xbfb8aa3b, v24
	v_mul_f32_e32 v22, v22, v71
	v_mul_f32_e32 v71, 0xbfb8aa3b, v71
	v_mul_f32_e32 v23, v23, v25
	v_mul_f32_e32 v25, 0xbfb8aa3b, v25
	v_exp_f32_e32 v29, v29
	v_exp_f32_e32 v24, v24
	v_exp_f32_e32 v71, v71
	v_exp_f32_e32 v25, v25
	v_add_f32_e32 v29, 1.0, v29
	v_add_f32_e32 v24, 1.0, v24
	v_add_f32_e32 v71, 1.0, v71
	v_add_f32_e32 v25, 1.0, v25
	v_rcp_f32_e32 v29, v29
	v_rcp_f32_e32 v24, v24
	v_rcp_f32_e32 v71, v71
	v_rcp_f32_e32 v25, v25
	v_mul_f32_e32 v20, v20, v29
	v_mul_f32_e32 v21, v21, v24
	v_mul_f32_e32 v22, v22, v71
	v_mul_f32_e32 v23, v23, v25
	v_cvt_pk_bf16_f32 v20, v20, v21
	v_cvt_pk_bf16_f32 v21, v22, v23
	global_store_dwordx2 v[64:65], v[20:21], off offset:512
	s_nop 0
	s_waitcnt vmcnt(7)
	v_lshlrev_b32_e32 v29, 16, v224
	v_and_b32_e32 v24, 0xffff0000, v224
	s_waitcnt vmcnt(7)
	v_mul_f32_e32 v20, v100, v200
	v_mul_f32_e32 v21, v101, v201
	v_lshlrev_b32_e32 v71, 16, v225
	v_and_b32_e32 v25, 0xffff0000, v225
	v_mul_f32_e32 v22, v102, v202
	v_mul_f32_e32 v23, v103, v203
	v_mul_f32_e32 v20, v20, v29
	v_mul_f32_e32 v29, 0xbfb8aa3b, v29
	v_mul_f32_e32 v21, v21, v24
	v_mul_f32_e32 v24, 0xbfb8aa3b, v24
	v_mul_f32_e32 v22, v22, v71
	v_mul_f32_e32 v71, 0xbfb8aa3b, v71
	v_mul_f32_e32 v23, v23, v25
	v_mul_f32_e32 v25, 0xbfb8aa3b, v25
	v_exp_f32_e32 v29, v29
	v_exp_f32_e32 v24, v24
	v_exp_f32_e32 v71, v71
	v_exp_f32_e32 v25, v25
	v_add_f32_e32 v29, 1.0, v29
	v_add_f32_e32 v24, 1.0, v24
	v_add_f32_e32 v71, 1.0, v71
	v_add_f32_e32 v25, 1.0, v25
	v_rcp_f32_e32 v29, v29
	v_rcp_f32_e32 v24, v24
	v_rcp_f32_e32 v71, v71
	v_rcp_f32_e32 v25, v25
	v_mul_f32_e32 v20, v20, v29
	v_mul_f32_e32 v21, v21, v24
	v_mul_f32_e32 v22, v22, v71
	v_mul_f32_e32 v23, v23, v25
	v_cvt_pk_bf16_f32 v20, v20, v21
	v_cvt_pk_bf16_f32 v21, v22, v23
	global_store_dwordx2 v[64:65], v[20:21], off offset:2560
	s_nop 0
	s_waitcnt vmcnt(7)
	v_lshlrev_b32_e32 v29, 16, v226
	v_and_b32_e32 v24, 0xffff0000, v226
	s_waitcnt vmcnt(7)
	v_mul_f32_e32 v21, v106, v205
	v_lshlrev_b32_e32 v71, 16, v227
	v_and_b32_e32 v25, 0xffff0000, v227
	v_mul_f32_e32 v22, v26, v206
	v_mul_f32_e32 v23, v27, v207
	v_mul_f32_e32 v26, 0xbfb8aa3b, v29
	v_mul_f32_e32 v21, v21, v24
	v_mul_f32_e32 v24, 0xbfb8aa3b, v24
	v_mul_f32_e32 v27, 0xbfb8aa3b, v71
	v_mul_f32_e32 v23, v23, v25
	v_mul_f32_e32 v25, 0xbfb8aa3b, v25
	v_exp_f32_e32 v26, v26
	v_exp_f32_e32 v24, v24
	v_exp_f32_e32 v27, v27
	v_exp_f32_e32 v25, v25
	v_add_f32_e32 v26, 1.0, v26
	v_add_f32_e32 v24, 1.0, v24
	v_add_f32_e32 v27, 1.0, v27
	v_add_f32_e32 v25, 1.0, v25
	v_rcp_f32_e32 v26, v26
	v_rcp_f32_e32 v24, v24
	v_rcp_f32_e32 v27, v27
	v_rcp_f32_e32 v25, v25
	v_mul_f32_e32 v20, v104, v204
	v_mul_f32_e32 v20, v20, v29
	v_mul_f32_e32 v22, v22, v71
	v_mul_f32_e32 v20, v20, v26
	v_mul_f32_e32 v21, v21, v24
	v_mul_f32_e32 v22, v22, v27
	v_mul_f32_e32 v23, v23, v25
	v_cvt_pk_bf16_f32 v20, v20, v21
	v_cvt_pk_bf16_f32 v21, v22, v23
	global_store_dwordx2 v[64:65], v[20:21], off offset:1024
	s_nop 0
	v_mul_f32_e32 v27, v83, v78
	v_mul_f32_e32 v26, v82, v78
	v_mul_f32_e32 v71, v80, v78
	v_mul_f32_e32 v29, v81, v78
	s_waitcnt vmcnt(7)
	v_lshlrev_b32_e32 v72, 16, v228
	v_and_b32_e32 v24, 0xffff0000, v228
	s_waitcnt vmcnt(7)
	v_mul_f32_e32 v21, v27, v209
	v_lshlrev_b32_e32 v73, 16, v229
	v_and_b32_e32 v25, 0xffff0000, v229
	v_mul_f32_e32 v20, v26, v208
	v_mul_f32_e32 v23, v71, v211
	v_mul_f32_e32 v26, 0xbfb8aa3b, v72
	v_mul_f32_e32 v21, v21, v24
	v_mul_f32_e32 v24, 0xbfb8aa3b, v24
	v_mul_f32_e32 v27, 0xbfb8aa3b, v73
	v_mul_f32_e32 v23, v23, v25
	v_mul_f32_e32 v25, 0xbfb8aa3b, v25
	v_exp_f32_e32 v26, v26
	v_exp_f32_e32 v24, v24
	v_exp_f32_e32 v27, v27
	v_exp_f32_e32 v25, v25
	v_add_f32_e32 v26, 1.0, v26
	v_add_f32_e32 v24, 1.0, v24
	v_add_f32_e32 v27, 1.0, v27
	v_add_f32_e32 v25, 1.0, v25
	v_rcp_f32_e32 v26, v26
	v_rcp_f32_e32 v24, v24
	v_rcp_f32_e32 v27, v27
	v_rcp_f32_e32 v25, v25
	v_mul_f32_e32 v22, v29, v210
	v_mul_f32_e32 v20, v20, v72
	v_mul_f32_e32 v22, v22, v73
	v_mul_f32_e32 v20, v20, v26
	v_mul_f32_e32 v21, v21, v24
	v_mul_f32_e32 v22, v22, v27
	v_mul_f32_e32 v23, v23, v25
	v_cvt_pk_bf16_f32 v20, v20, v21
	v_cvt_pk_bf16_f32 v21, v22, v23
	global_store_dwordx2 v[64:65], v[20:21], off offset:3072
	s_nop 0
	s_waitcnt vmcnt(7)
	v_lshlrev_b32_e32 v26, 16, v230
	v_and_b32_e32 v24, 0xffff0000, v230
	v_lshlrev_b32_e32 v27, 16, v231
	v_and_b32_e32 v25, 0xffff0000, v231
	s_waitcnt vmcnt(7)
	v_mul_f32_e32 v16, v16, v212
	v_mul_f32_e32 v17, v17, v213
	v_mul_f32_e32 v20, 0xbfb8aa3b, v26
	v_mul_f32_e32 v21, 0xbfb8aa3b, v24
	v_mul_f32_e32 v18, v18, v214
	v_mul_f32_e32 v19, v19, v215
	v_mul_f32_e32 v22, 0xbfb8aa3b, v27
	v_mul_f32_e32 v23, 0xbfb8aa3b, v25
	v_exp_f32_e32 v20, v20
	v_exp_f32_e32 v21, v21
	v_exp_f32_e32 v22, v22
	v_exp_f32_e32 v23, v23
	v_add_f32_e32 v20, 1.0, v20
	v_add_f32_e32 v21, 1.0, v21
	v_add_f32_e32 v22, 1.0, v22
	v_add_f32_e32 v23, 1.0, v23
	v_rcp_f32_e32 v20, v20
	v_rcp_f32_e32 v21, v21
	v_rcp_f32_e32 v22, v22
	v_rcp_f32_e32 v23, v23
	v_mul_f32_e32 v16, v16, v26
	v_mul_f32_e32 v17, v17, v24
	v_mul_f32_e32 v18, v18, v27
	v_mul_f32_e32 v19, v19, v25
	v_mul_f32_e32 v16, v16, v20
	v_mul_f32_e32 v17, v17, v21
	v_mul_f32_e32 v18, v18, v22
	v_mul_f32_e32 v19, v19, v23
	v_cvt_pk_bf16_f32 v16, v16, v17
	v_cvt_pk_bf16_f32 v17, v18, v19
	global_store_dwordx2 v[64:65], v[16:17], off offset:1536
	s_nop 0
	v_mul_f32_e32 v23, v79, v78
	v_mul_f32_e32 v22, v77, v78
	v_mul_f32_e32 v25, v74, v78
	v_mul_f32_e32 v24, v70, v78
	s_waitcnt vmcnt(7)
	v_lshlrev_b32_e32 v26, 16, v232
	v_and_b32_e32 v20, 0xffff0000, v232
	s_waitcnt vmcnt(7)
	v_mul_f32_e32 v17, v23, v217
	v_lshlrev_b32_e32 v27, 16, v233
	v_and_b32_e32 v21, 0xffff0000, v233
	v_mul_f32_e32 v16, v22, v216
	v_mul_f32_e32 v19, v25, v219
	v_mul_f32_e32 v22, 0xbfb8aa3b, v26
	v_mul_f32_e32 v17, v17, v20
	v_mul_f32_e32 v20, 0xbfb8aa3b, v20
	v_mul_f32_e32 v23, 0xbfb8aa3b, v27
	v_mul_f32_e32 v19, v19, v21
	v_mul_f32_e32 v21, 0xbfb8aa3b, v21
	v_exp_f32_e32 v22, v22
	v_exp_f32_e32 v20, v20
	v_exp_f32_e32 v23, v23
	v_exp_f32_e32 v21, v21
	v_add_f32_e32 v22, 1.0, v22
	v_add_f32_e32 v20, 1.0, v20
	v_add_f32_e32 v23, 1.0, v23
	v_add_f32_e32 v21, 1.0, v21
	v_rcp_f32_e32 v22, v22
	v_rcp_f32_e32 v20, v20
	v_rcp_f32_e32 v23, v23
	v_rcp_f32_e32 v21, v21
	v_mul_f32_e32 v18, v24, v218
	v_mul_f32_e32 v16, v16, v26
	v_mul_f32_e32 v18, v18, v27
	v_mul_f32_e32 v16, v16, v22
	v_mul_f32_e32 v17, v17, v20
	v_mul_f32_e32 v18, v18, v23
	v_mul_f32_e32 v19, v19, v21
	v_cvt_pk_bf16_f32 v16, v16, v17
	v_cvt_pk_bf16_f32 v17, v18, v19
	global_store_dwordx2 v[64:65], v[16:17], off offset:3584
	s_cbranch_scc0 .LBB0_489
	s_add_i32 s56, s56, s58
	s_add_i32 s8, s8, s15
	s_cmpk_gt_i32 s56, 0x7ff
	s_cbranch_scc0 .LBB0_488
